# mode-1 scan: the 8 steps of a sub-block unrolled, one FIFO stream of LDS quad reads through a ring of 12 register quads (12 reads ahead), at most 15 LDS ops outstanding
# speedup vs baseline: 1.0095x; 1.0020x over previous
; template <int MODE> __device__ __forceinline__ void rwkv_item(const Params& P, int e, int c, int h, LAS float* slab, int lane) {
;     ...
;             if (NB == 2) RW_LD_DOT(0, 0);
;             const float v = st[320 + lane];
; #pragma unroll
;             for (int hb = 0; hb < NDB; ++hb) {
;                 if (NB == 2) { if (hb + 1 < NDB) RW_LD_DOT((hb + 1) & 1, hb + 1); else RW_LD_UPD(0, 0); } else RW_LD_DOT(0, hb);
;                 __builtin_amdgcn_sched_barrier(0);
; #pragma unroll
;                 for (int q = 0; q < DB; ++q) {
;                     const int qq = DB * hb + q; const f32x4 k4 = kd[hb & (NB - 1)][q];
;                     aS0 += S2[2 * qq] * (f32x2){k4.x, k4.y}; aS1 += S2[2 * qq + 1] * (f32x2){k4.z, k4.w};
;                     if (MODE == 0) { aC0 += C2[2 * qq] * (f32x2){k4.x, k4.y}; aC1 += C2[2 * qq + 1] * (f32x2){k4.z, k4.w}; }
;                 }
;                 __builtin_amdgcn_sched_barrier(0);
;             }
;             const float nsk = -((aS0.x + aS0.y) + (aS1.x + aS1.y));
;             const float nskC = -((aC0.x + aC0.y) + (aC1.x + aC1.y));
;             f32x2 y0 = {0.f, 0.f}, y1 = {0.f, 0.f};
; #pragma unroll
;             for (int qb = 0; qb < NUB; ++qb) {
;                 if (NB == 2) { if (qb + 1 < NUB) RW_LD_UPD((qb + 1) & 1, qb + 1); } else RW_LD_UPD(0, qb);
;                 __builtin_amdgcn_sched_barrier(0);
; #pragma unroll
;                 for (int q = 0; q < UB; ++q) {
;                     const int qq = UB * qb + q;
;                     const f32x4 w4 = wq[qb & (NB - 1)][q], b4 = bq[qb & (NB - 1)][q], k4 = kq[qb & (NB - 1)][q];
;                     if (MODE == 0) {
;                         S2[2 * qq] = S2[2 * qq] * (f32x2){w4.x, w4.y} + (f32x2){b4.x, b4.y} * nsk;
;                         S2[2 * qq + 1] = S2[2 * qq + 1] * (f32x2){w4.z, w4.w} + (f32x2){b4.z, b4.w} * nsk;
;                         C2[2 * qq] = C2[2 * qq] * (f32x2){w4.x, w4.y} + (f32x2){b4.x, b4.y} * nskC + (f32x2){k4.x, k4.y} * v;
;                         C2[2 * qq + 1] = C2[2 * qq + 1] * (f32x2){w4.z, w4.w} + (f32x2){b4.z, b4.w} * nskC + (f32x2){k4.z, k4.w} * v;
;                     } else {
;                         S2[2 * qq] = S2[2 * qq] * (f32x2){w4.x, w4.y} + (f32x2){b4.x, b4.y} * nsk + (f32x2){k4.x, k4.y} * v;
.Lm1_noload:
	s_waitcnt lgkmcnt(0)
	s_mov_b32 s11, 0
	v_mov_b32_e32 v196, s3
	v_mov_b32_e32 v199, v213
	ds_read_b128 v[136:139], v196 offset:256
	ds_read_b128 v[140:143], v196 offset:272
	ds_read_b128 v[144:147], v196 offset:288
	ds_read_b128 v[148:151], v196 offset:304
	ds_read_b128 v[176:179], v196 offset:320
	ds_read_b128 v[180:183], v196 offset:336
	ds_read_b128 v[184:187], v196 offset:352
	ds_read_b128 v[188:191], v196 offset:368
	ds_read_b128 v[200:203], v196 offset:384
	ds_read_b128 v[204:207], v196 offset:400
	ds_read_b128 v[214:217], v196 offset:416
	ds_read_b128 v[238:241], v196 offset:432
	s_waitcnt lgkmcnt(10)
	ds_read_b32 v194, v109 offset:1280
	ds_read_b128 v[124:127], v199 offset:512
	ds_read_b128 v[230:233], v199 offset:768
	ds_read_b128 v[128:131], v199 offset:528
	ds_read_b128 v[234:237], v199 offset:784
	v_pk_fma_f32 v[158:159], v[0:1], v[136:137], 0 op_sel_hi:[1,1,0]
	v_pk_fma_f32 v[160:161], v[2:3], v[138:139], 0 op_sel_hi:[1,1,0]
	s_waitcnt lgkmcnt(14)
	ds_read_b128 v[136:139], v196 offset:448
	v_pk_fma_f32 v[162:163], v[4:5], v[140:141], 0 op_sel_hi:[1,1,0]
	v_pk_fma_f32 v[164:165], v[6:7], v[142:143], 0 op_sel_hi:[1,1,0]
	s_waitcnt lgkmcnt(14)
	ds_read_b128 v[140:143], v196 offset:464
	v_pk_fma_f32 v[158:159], v[8:9], v[144:145], v[158:159]
	v_pk_fma_f32 v[160:161], v[10:11], v[146:147], v[160:161]
	s_waitcnt lgkmcnt(14)
	ds_read_b128 v[144:147], v196 offset:480
	v_pk_fma_f32 v[162:163], v[12:13], v[148:149], v[162:163]
	v_pk_fma_f32 v[164:165], v[14:15], v[150:151], v[164:165]
	s_waitcnt lgkmcnt(14)
	ds_read_b128 v[148:151], v196 offset:496
	v_pk_fma_f32 v[158:159], v[16:17], v[176:177], v[158:159]
	v_pk_fma_f32 v[160:161], v[18:19], v[178:179], v[160:161]
	s_waitcnt lgkmcnt(14)
	ds_read_b128 v[176:179], v196 offset:1024
	v_pk_fma_f32 v[162:163], v[20:21], v[180:181], v[162:163]
	v_pk_fma_f32 v[164:165], v[22:23], v[182:183], v[164:165]
	s_waitcnt lgkmcnt(14)
	ds_read_b128 v[180:183], v196 offset:1040
	v_pk_fma_f32 v[158:159], v[24:25], v[184:185], v[158:159]
	v_pk_fma_f32 v[160:161], v[26:27], v[186:187], v[160:161]
	s_waitcnt lgkmcnt(14)
	ds_read_b128 v[184:187], v196 offset:1056
	v_pk_fma_f32 v[162:163], v[28:29], v[188:189], v[162:163]
	v_pk_fma_f32 v[164:165], v[30:31], v[190:191], v[164:165]
	s_waitcnt lgkmcnt(14)
	ds_read_b128 v[188:191], v196 offset:1072
	v_pk_fma_f32 v[158:159], v[32:33], v[200:201], v[158:159]
	v_pk_fma_f32 v[160:161], v[34:35], v[202:203], v[160:161]
	s_waitcnt lgkmcnt(14)
	ds_read_b128 v[200:203], v196 offset:1088
	v_pk_fma_f32 v[162:163], v[36:37], v[204:205], v[162:163]
	v_pk_fma_f32 v[164:165], v[38:39], v[206:207], v[164:165]
	s_waitcnt lgkmcnt(14)
	ds_read_b128 v[204:207], v196 offset:1104
	v_pk_fma_f32 v[158:159], v[40:41], v[214:215], v[158:159]
	v_pk_fma_f32 v[160:161], v[42:43], v[216:217], v[160:161]
	s_waitcnt lgkmcnt(14)
	ds_read_b128 v[214:217], v196 offset:1120
	v_pk_fma_f32 v[162:163], v[44:45], v[238:239], v[162:163]
	v_pk_fma_f32 v[164:165], v[46:47], v[240:241], v[164:165]
	s_waitcnt lgkmcnt(14)
	ds_read_b128 v[238:241], v196 offset:1136
	s_waitcnt lgkmcnt(11)
	v_pk_fma_f32 v[158:159], v[48:49], v[136:137], v[158:159]
	v_pk_fma_f32 v[160:161], v[50:51], v[138:139], v[160:161]
	ds_read_b128 v[136:139], v196 offset:1152
	s_waitcnt lgkmcnt(11)
	v_pk_fma_f32 v[162:163], v[52:53], v[140:141], v[162:163]
	v_pk_fma_f32 v[164:165], v[54:55], v[142:143], v[164:165]
	ds_read_b128 v[140:143], v196 offset:1168
	s_waitcnt lgkmcnt(11)
	v_pk_fma_f32 v[158:159], v[56:57], v[144:145], v[158:159]
	v_pk_fma_f32 v[160:161], v[58:59], v[146:147], v[160:161]
	ds_read_b128 v[144:147], v196 offset:1184
	s_waitcnt lgkmcnt(11)
	v_pk_fma_f32 v[162:163], v[60:61], v[148:149], v[162:163]
	v_pk_fma_f32 v[164:165], v[62:63], v[150:151], v[164:165]
	ds_read_b128 v[148:151], v196 offset:1200
	v_pk_add_f32 v[158:159], v[158:159], v[162:163]
	v_pk_add_f32 v[160:161], v[160:161], v[164:165]
	v_add_f32_e32 v192, v158, v159
	v_add_f32_e32 v198, v160, v161
	v_sub_f32_e64 v193, -v198, v192
	s_nop 1
	v_mfma_f32_4x4x1_16b_f32 v[0:3], v124, v193, v[0:3]
	v_mfma_f32_4x4x1_16b_f32 v[4:7], v125, v193, v[4:7]
	v_mfma_f32_4x4x1_16b_f32 v[0:3], v230, v194, v[0:3]
	v_mfma_f32_4x4x1_16b_f32 v[8:11], v126, v193, v[8:11]
	v_mfma_f32_4x4x1_16b_f32 v[4:7], v231, v194, v[4:7]
	v_mfma_f32_4x4x1_16b_f32 v[12:15], v127, v193, v[12:15]
	v_mfma_f32_4x4x1_16b_f32 v[8:11], v232, v194, v[8:11]
	ds_read_b128 v[124:127], v199 offset:544
	v_mfma_f32_4x4x1_16b_f32 v[16:19], v128, v193, v[16:19]
	v_mfma_f32_4x4x1_16b_f32 v[12:15], v233, v194, v[12:15]
	ds_read_b128 v[230:233], v199 offset:800
	v_mfma_f32_4x4x1_16b_f32 v[20:23], v129, v193, v[20:23]
	v_mfma_f32_4x4x1_16b_f32 v[16:19], v234, v194, v[16:19]
	v_mfma_f32_4x4x1_16b_f32 v[24:27], v130, v193, v[24:27]
	v_mfma_f32_4x4x1_16b_f32 v[20:23], v235, v194, v[20:23]
	v_mfma_f32_4x4x1_16b_f32 v[28:31], v131, v193, v[28:31]
	v_mfma_f32_4x4x1_16b_f32 v[24:27], v236, v194, v[24:27]
	ds_read_b128 v[128:131], v199 offset:560
	s_waitcnt lgkmcnt(2)
	v_mfma_f32_4x4x1_16b_f32 v[32:35], v124, v193, v[32:35]
	v_mfma_f32_4x4x1_16b_f32 v[28:31], v237, v194, v[28:31]
	ds_read_b128 v[234:237], v199 offset:816
	v_mfma_f32_4x4x1_16b_f32 v[36:39], v125, v193, v[36:39]
	s_waitcnt lgkmcnt(2)
	v_mfma_f32_4x4x1_16b_f32 v[32:35], v230, v194, v[32:35]
	v_mfma_f32_4x4x1_16b_f32 v[40:43], v126, v193, v[40:43]
	v_mfma_f32_4x4x1_16b_f32 v[36:39], v231, v194, v[36:39]
	v_mfma_f32_4x4x1_16b_f32 v[44:47], v127, v193, v[44:47]
	v_mfma_f32_4x4x1_16b_f32 v[40:43], v232, v194, v[40:43]
	s_waitcnt lgkmcnt(1)
	v_mfma_f32_4x4x1_16b_f32 v[48:51], v128, v193, v[48:51]
	v_mfma_f32_4x4x1_16b_f32 v[44:47], v233, v194, v[44:47]
	v_mfma_f32_4x4x1_16b_f32 v[52:55], v129, v193, v[52:55]
	s_waitcnt lgkmcnt(0)
; #define LAS __attribute__((address_space(3)))
; #define RW_LD_UPD(buf, qb) do { _Pragma("unroll") for (int q_ = 0; q_ < UB; ++q_) { const int qq_ = UB * (qb) + q_; \
;                 wq[buf][q_] = *(const LAS f32x4*)(st + 4 * qq_); bq[buf][q_] = *(const LAS f32x4*)(st + 128 + 4 * qq_); kq[buf][q_] = *(const LAS f32x4*)(st + 192 + 4 * qq_); \
;                 if (MODE == 1) rq[buf][q_] = *(const LAS f32x4*)(st + 256 + 4 * qq_); } } while (0)
; template <int MODE> __device__ __forceinline__ void rwkv_item(const Params& P, int e, int c, int h, LAS float* slab, int lane) {
;     ...
;             f32x2 y0 = {0.f, 0.f}, y1 = {0.f, 0.f};
; #pragma unroll
;             for (int qb = 0; qb < NUB; ++qb) {
;                 if (NB == 2) { if (qb + 1 < NUB) RW_LD_UPD((qb + 1) & 1, qb + 1); } else RW_LD_UPD(0, qb);
;                 __builtin_amdgcn_sched_barrier(0);
; #pragma unroll
;                 for (int q = 0; q < UB; ++q) {
;                     const int qq = UB * qb + q;
;                     const f32x4 w4 = wq[qb & (NB - 1)][q], b4 = bq[qb & (NB - 1)][q], k4 = kq[qb & (NB - 1)][q];
;                     if (MODE == 0) {
;                         S2[2 * qq] = S2[2 * qq] * (f32x2){w4.x, w4.y} + (f32x2){b4.x, b4.y} * nsk;
;                         S2[2 * qq + 1] = S2[2 * qq + 1] * (f32x2){w4.z, w4.w} + (f32x2){b4.z, b4.w} * nsk;
;                         C2[2 * qq] = C2[2 * qq] * (f32x2){w4.x, w4.y} + (f32x2){b4.x, b4.y} * nskC + (f32x2){k4.x, k4.y} * v;
;                         C2[2 * qq + 1] = C2[2 * qq + 1] * (f32x2){w4.z, w4.w} + (f32x2){b4.z, b4.w} * nskC + (f32x2){k4.z, k4.w} * v;
;                     } else {
;                         S2[2 * qq] = S2[2 * qq] * (f32x2){w4.x, w4.y} + (f32x2){b4.x, b4.y} * nsk + (f32x2){k4.x, k4.y} * v;
;                         S2[2 * qq + 1] = S2[2 * qq + 1] * (f32x2){w4.z, w4.w} + (f32x2){b4.z, b4.w} * nsk + (f32x2){k4.z, k4.w} * v;
;                         const f32x4 r4 = rq[qb & (NB - 1)][q]; y0 += S2[2 * qq] * (f32x2){r4.x, r4.y}; y1 += S2[2 * qq + 1] * (f32x2){r4.z, r4.w};
;                     }
;                 }
;                 __builtin_amdgcn_sched_barrier(0);
;             }
;     ...
;             if (MODE == 1) ((LAS float*)st)[lane] = (y0.x + y0.y) + (y1.x + y1.y);
	v_mfma_f32_4x4x1_16b_f32 v[48:51], v234, v194, v[48:51]
	v_mfma_f32_4x4x1_16b_f32 v[56:59], v130, v193, v[56:59]
	v_mfma_f32_4x4x1_16b_f32 v[52:55], v235, v194, v[52:55]
	v_mfma_f32_4x4x1_16b_f32 v[60:63], v131, v193, v[60:63]
	v_mfma_f32_4x4x1_16b_f32 v[56:59], v236, v194, v[56:59]
	s_nop 0
	v_mfma_f32_4x4x1_16b_f32 v[60:63], v237, v194, v[60:63]
	v_pk_fma_f32 v[158:159], v[176:177], v[0:1], 0 op_sel_hi:[1,1,0]
	v_pk_fma_f32 v[160:161], v[178:179], v[2:3], 0 op_sel_hi:[1,1,0]
	ds_read_b128 v[176:179], v196 offset:1216
	v_pk_fma_f32 v[162:163], v[180:181], v[4:5], 0 op_sel_hi:[1,1,0]
	v_pk_fma_f32 v[164:165], v[182:183], v[6:7], 0 op_sel_hi:[1,1,0]
	ds_read_b128 v[180:183], v196 offset:1232
	v_pk_fma_f32 v[158:159], v[184:185], v[8:9], v[158:159]
	v_pk_fma_f32 v[160:161], v[186:187], v[10:11], v[160:161]
	ds_read_b128 v[184:187], v196 offset:1248
	v_pk_fma_f32 v[162:163], v[188:189], v[12:13], v[162:163]
	v_pk_fma_f32 v[164:165], v[190:191], v[14:15], v[164:165]
	ds_read_b128 v[188:191], v196 offset:1264
	v_pk_fma_f32 v[158:159], v[200:201], v[16:17], v[158:159]
	v_pk_fma_f32 v[160:161], v[202:203], v[18:19], v[160:161]
	ds_read_b128 v[200:203], v196 offset:2304
	v_pk_fma_f32 v[162:163], v[204:205], v[20:21], v[162:163]
	v_pk_fma_f32 v[164:165], v[206:207], v[22:23], v[164:165]
	ds_read_b128 v[204:207], v196 offset:2320
	v_pk_fma_f32 v[158:159], v[214:215], v[24:25], v[158:159]
	v_pk_fma_f32 v[160:161], v[216:217], v[26:27], v[160:161]
	ds_read_b128 v[214:217], v196 offset:2336
	v_pk_fma_f32 v[162:163], v[238:239], v[28:29], v[162:163]
	v_pk_fma_f32 v[164:165], v[240:241], v[30:31], v[164:165]
	ds_read_b128 v[238:241], v196 offset:2352
	v_pk_fma_f32 v[158:159], v[136:137], v[32:33], v[158:159]
	v_pk_fma_f32 v[160:161], v[138:139], v[34:35], v[160:161]
	ds_read_b128 v[136:139], v196 offset:2368
	v_pk_fma_f32 v[162:163], v[140:141], v[36:37], v[162:163]
	v_pk_fma_f32 v[164:165], v[142:143], v[38:39], v[164:165]
	ds_read_b128 v[140:143], v196 offset:2384
	v_pk_fma_f32 v[158:159], v[144:145], v[40:41], v[158:159]
	v_pk_fma_f32 v[160:161], v[146:147], v[42:43], v[160:161]
	ds_read_b128 v[144:147], v196 offset:2400
	v_pk_fma_f32 v[162:163], v[148:149], v[44:45], v[162:163]
	v_pk_fma_f32 v[164:165], v[150:151], v[46:47], v[164:165]
	ds_read_b128 v[148:151], v196 offset:2416
	s_waitcnt lgkmcnt(11)
	v_pk_fma_f32 v[158:159], v[176:177], v[48:49], v[158:159]
	v_pk_fma_f32 v[160:161], v[178:179], v[50:51], v[160:161]
	ds_read_b128 v[176:179], v196 offset:2432
	s_waitcnt lgkmcnt(11)
	v_pk_fma_f32 v[162:163], v[180:181], v[52:53], v[162:163]
	v_pk_fma_f32 v[164:165], v[182:183], v[54:55], v[164:165]
	ds_read_b128 v[180:183], v196 offset:2448
	s_waitcnt lgkmcnt(11)
	v_pk_fma_f32 v[158:159], v[184:185], v[56:57], v[158:159]
	v_pk_fma_f32 v[160:161], v[186:187], v[58:59], v[160:161]
	ds_read_b128 v[184:187], v196 offset:2464
	s_waitcnt lgkmcnt(11)
	v_pk_fma_f32 v[162:163], v[188:189], v[60:61], v[162:163]
	v_pk_fma_f32 v[164:165], v[190:191], v[62:63], v[164:165]
	ds_read_b128 v[188:191], v196 offset:2480
	v_pk_add_f32 v[158:159], v[158:159], v[162:163]
	v_pk_add_f32 v[160:161], v[160:161], v[164:165]
	v_add_f32_e32 v198, v158, v159
	v_add_f32_e32 v192, v160, v161
	v_add_f32_e32 v198, v192, v198
	ds_write_b32 v109, v198
	s_waitcnt lgkmcnt(10)
	ds_read_b32 v194, v109 offset:3328
	ds_read_b128 v[124:127], v199 offset:2560
	ds_read_b128 v[230:233], v199 offset:2816
	ds_read_b128 v[128:131], v199 offset:2576
	ds_read_b128 v[234:237], v199 offset:2832
	v_pk_fma_f32 v[158:159], v[0:1], v[200:201], 0 op_sel_hi:[1,1,0]
	v_pk_fma_f32 v[160:161], v[2:3], v[202:203], 0 op_sel_hi:[1,1,0]
	s_waitcnt lgkmcnt(14)
	ds_read_b128 v[200:203], v196 offset:2496
	v_pk_fma_f32 v[162:163], v[4:5], v[204:205], 0 op_sel_hi:[1,1,0]
	v_pk_fma_f32 v[164:165], v[6:7], v[206:207], 0 op_sel_hi:[1,1,0]
	s_waitcnt lgkmcnt(14)
	ds_read_b128 v[204:207], v196 offset:2512
	v_pk_fma_f32 v[158:159], v[8:9], v[214:215], v[158:159]
	v_pk_fma_f32 v[160:161], v[10:11], v[216:217], v[160:161]
	s_waitcnt lgkmcnt(14)
	ds_read_b128 v[214:217], v196 offset:2528
	v_pk_fma_f32 v[162:163], v[12:13], v[238:239], v[162:163]
	v_pk_fma_f32 v[164:165], v[14:15], v[240:241], v[164:165]
	s_waitcnt lgkmcnt(14)
	ds_read_b128 v[238:241], v196 offset:2544
	v_pk_fma_f32 v[158:159], v[16:17], v[136:137], v[158:159]
	v_pk_fma_f32 v[160:161], v[18:19], v[138:139], v[160:161]
	s_waitcnt lgkmcnt(14)
	ds_read_b128 v[136:139], v196 offset:3072
	v_pk_fma_f32 v[162:163], v[20:21], v[140:141], v[162:163]
	v_pk_fma_f32 v[164:165], v[22:23], v[142:143], v[164:165]
	s_waitcnt lgkmcnt(14)
	ds_read_b128 v[140:143], v196 offset:3088
	v_pk_fma_f32 v[158:159], v[24:25], v[144:145], v[158:159]
	v_pk_fma_f32 v[160:161], v[26:27], v[146:147], v[160:161]
	s_waitcnt lgkmcnt(14)
	ds_read_b128 v[144:147], v196 offset:3104
	v_pk_fma_f32 v[162:163], v[28:29], v[148:149], v[162:163]
	v_pk_fma_f32 v[164:165], v[30:31], v[150:151], v[164:165]
	s_waitcnt lgkmcnt(14)
	ds_read_b128 v[148:151], v196 offset:3120
	v_pk_fma_f32 v[158:159], v[32:33], v[176:177], v[158:159]
	v_pk_fma_f32 v[160:161], v[34:35], v[178:179], v[160:161]
	s_waitcnt lgkmcnt(14)
	ds_read_b128 v[176:179], v196 offset:3136
	v_pk_fma_f32 v[162:163], v[36:37], v[180:181], v[162:163]
	v_pk_fma_f32 v[164:165], v[38:39], v[182:183], v[164:165]
	s_waitcnt lgkmcnt(14)
	ds_read_b128 v[180:183], v196 offset:3152
	v_pk_fma_f32 v[158:159], v[40:41], v[184:185], v[158:159]
	v_pk_fma_f32 v[160:161], v[42:43], v[186:187], v[160:161]
	s_waitcnt lgkmcnt(14)
	ds_read_b128 v[184:187], v196 offset:3168
	v_pk_fma_f32 v[162:163], v[44:45], v[188:189], v[162:163]
	v_pk_fma_f32 v[164:165], v[46:47], v[190:191], v[164:165]
	s_waitcnt lgkmcnt(14)
; template <int MODE> __device__ __forceinline__ void rwkv_item(const Params& P, int e, int c, int h, LAS float* slab, int lane) {
;     ...
;             if (NB == 2) RW_LD_DOT(0, 0);
;             const float v = st[320 + lane];
; #pragma unroll
;             for (int hb = 0; hb < NDB; ++hb) {
;                 if (NB == 2) { if (hb + 1 < NDB) RW_LD_DOT((hb + 1) & 1, hb + 1); else RW_LD_UPD(0, 0); } else RW_LD_DOT(0, hb);
;                 __builtin_amdgcn_sched_barrier(0);
; #pragma unroll
;                 for (int q = 0; q < DB; ++q) {
;                     const int qq = DB * hb + q; const f32x4 k4 = kd[hb & (NB - 1)][q];
;                     aS0 += S2[2 * qq] * (f32x2){k4.x, k4.y}; aS1 += S2[2 * qq + 1] * (f32x2){k4.z, k4.w};
;                     if (MODE == 0) { aC0 += C2[2 * qq] * (f32x2){k4.x, k4.y}; aC1 += C2[2 * qq + 1] * (f32x2){k4.z, k4.w}; }
;                 }
;                 __builtin_amdgcn_sched_barrier(0);
;             }
;             const float nsk = -((aS0.x + aS0.y) + (aS1.x + aS1.y));
;             const float nskC = -((aC0.x + aC0.y) + (aC1.x + aC1.y));
;             f32x2 y0 = {0.f, 0.f}, y1 = {0.f, 0.f};
; #pragma unroll
;             for (int qb = 0; qb < NUB; ++qb) {
;                 if (NB == 2) { if (qb + 1 < NUB) RW_LD_UPD((qb + 1) & 1, qb + 1); } else RW_LD_UPD(0, qb);
;                 __builtin_amdgcn_sched_barrier(0);
; #pragma unroll
;                 for (int q = 0; q < UB; ++q) {
;                     const int qq = UB * qb + q;
;                     const f32x4 w4 = wq[qb & (NB - 1)][q], b4 = bq[qb & (NB - 1)][q], k4 = kq[qb & (NB - 1)][q];
;                     if (MODE == 0) {
;                         S2[2 * qq] = S2[2 * qq] * (f32x2){w4.x, w4.y} + (f32x2){b4.x, b4.y} * nsk;
;                         S2[2 * qq + 1] = S2[2 * qq + 1] * (f32x2){w4.z, w4.w} + (f32x2){b4.z, b4.w} * nsk;
;                         C2[2 * qq] = C2[2 * qq] * (f32x2){w4.x, w4.y} + (f32x2){b4.x, b4.y} * nskC + (f32x2){k4.x, k4.y} * v;
;                         C2[2 * qq + 1] = C2[2 * qq + 1] * (f32x2){w4.z, w4.w} + (f32x2){b4.z, b4.w} * nskC + (f32x2){k4.z, k4.w} * v;
;                     } else {
;                         S2[2 * qq] = S2[2 * qq] * (f32x2){w4.x, w4.y} + (f32x2){b4.x, b4.y} * nsk + (f32x2){k4.x, k4.y} * v;
	ds_read_b128 v[188:191], v196 offset:3184
	s_waitcnt lgkmcnt(11)
	v_pk_fma_f32 v[158:159], v[48:49], v[200:201], v[158:159]
	v_pk_fma_f32 v[160:161], v[50:51], v[202:203], v[160:161]
	ds_read_b128 v[200:203], v196 offset:3200
	s_waitcnt lgkmcnt(11)
	v_pk_fma_f32 v[162:163], v[52:53], v[204:205], v[162:163]
	v_pk_fma_f32 v[164:165], v[54:55], v[206:207], v[164:165]
	ds_read_b128 v[204:207], v196 offset:3216
	s_waitcnt lgkmcnt(11)
	v_pk_fma_f32 v[158:159], v[56:57], v[214:215], v[158:159]
	v_pk_fma_f32 v[160:161], v[58:59], v[216:217], v[160:161]
	ds_read_b128 v[214:217], v196 offset:3232
	s_waitcnt lgkmcnt(11)
	v_pk_fma_f32 v[162:163], v[60:61], v[238:239], v[162:163]
	v_pk_fma_f32 v[164:165], v[62:63], v[240:241], v[164:165]
	ds_read_b128 v[238:241], v196 offset:3248
	v_pk_add_f32 v[158:159], v[158:159], v[162:163]
	v_pk_add_f32 v[160:161], v[160:161], v[164:165]
	v_add_f32_e32 v192, v158, v159
	v_add_f32_e32 v198, v160, v161
	v_sub_f32_e64 v193, -v198, v192
	s_nop 1
	v_mfma_f32_4x4x1_16b_f32 v[0:3], v124, v193, v[0:3]
	v_mfma_f32_4x4x1_16b_f32 v[4:7], v125, v193, v[4:7]
	v_mfma_f32_4x4x1_16b_f32 v[0:3], v230, v194, v[0:3]
	v_mfma_f32_4x4x1_16b_f32 v[8:11], v126, v193, v[8:11]
	v_mfma_f32_4x4x1_16b_f32 v[4:7], v231, v194, v[4:7]
	v_mfma_f32_4x4x1_16b_f32 v[12:15], v127, v193, v[12:15]
	v_mfma_f32_4x4x1_16b_f32 v[8:11], v232, v194, v[8:11]
	ds_read_b128 v[124:127], v199 offset:2592
	v_mfma_f32_4x4x1_16b_f32 v[16:19], v128, v193, v[16:19]
	v_mfma_f32_4x4x1_16b_f32 v[12:15], v233, v194, v[12:15]
	ds_read_b128 v[230:233], v199 offset:2848
	v_mfma_f32_4x4x1_16b_f32 v[20:23], v129, v193, v[20:23]
	v_mfma_f32_4x4x1_16b_f32 v[16:19], v234, v194, v[16:19]
	v_mfma_f32_4x4x1_16b_f32 v[24:27], v130, v193, v[24:27]
	v_mfma_f32_4x4x1_16b_f32 v[20:23], v235, v194, v[20:23]
	v_mfma_f32_4x4x1_16b_f32 v[28:31], v131, v193, v[28:31]
	v_mfma_f32_4x4x1_16b_f32 v[24:27], v236, v194, v[24:27]
	ds_read_b128 v[128:131], v199 offset:2608
	s_waitcnt lgkmcnt(2)
	v_mfma_f32_4x4x1_16b_f32 v[32:35], v124, v193, v[32:35]
	v_mfma_f32_4x4x1_16b_f32 v[28:31], v237, v194, v[28:31]
	ds_read_b128 v[234:237], v199 offset:2864
	v_mfma_f32_4x4x1_16b_f32 v[36:39], v125, v193, v[36:39]
	s_waitcnt lgkmcnt(2)
	v_mfma_f32_4x4x1_16b_f32 v[32:35], v230, v194, v[32:35]
	v_mfma_f32_4x4x1_16b_f32 v[40:43], v126, v193, v[40:43]
	v_mfma_f32_4x4x1_16b_f32 v[36:39], v231, v194, v[36:39]
	v_mfma_f32_4x4x1_16b_f32 v[44:47], v127, v193, v[44:47]
	v_mfma_f32_4x4x1_16b_f32 v[40:43], v232, v194, v[40:43]
	s_waitcnt lgkmcnt(1)
	v_mfma_f32_4x4x1_16b_f32 v[48:51], v128, v193, v[48:51]
	v_mfma_f32_4x4x1_16b_f32 v[44:47], v233, v194, v[44:47]
	v_mfma_f32_4x4x1_16b_f32 v[52:55], v129, v193, v[52:55]
	s_waitcnt lgkmcnt(0)
	v_mfma_f32_4x4x1_16b_f32 v[48:51], v234, v194, v[48:51]
	v_mfma_f32_4x4x1_16b_f32 v[56:59], v130, v193, v[56:59]
	v_mfma_f32_4x4x1_16b_f32 v[52:55], v235, v194, v[52:55]
	v_mfma_f32_4x4x1_16b_f32 v[60:63], v131, v193, v[60:63]
	v_mfma_f32_4x4x1_16b_f32 v[56:59], v236, v194, v[56:59]
	s_nop 0
	v_mfma_f32_4x4x1_16b_f32 v[60:63], v237, v194, v[60:63]
	v_pk_fma_f32 v[158:159], v[136:137], v[0:1], 0 op_sel_hi:[1,1,0]
	v_pk_fma_f32 v[160:161], v[138:139], v[2:3], 0 op_sel_hi:[1,1,0]
	ds_read_b128 v[136:139], v196 offset:3264
	v_pk_fma_f32 v[162:163], v[140:141], v[4:5], 0 op_sel_hi:[1,1,0]
	v_pk_fma_f32 v[164:165], v[142:143], v[6:7], 0 op_sel_hi:[1,1,0]
	ds_read_b128 v[140:143], v196 offset:3280
	v_pk_fma_f32 v[158:159], v[144:145], v[8:9], v[158:159]
	v_pk_fma_f32 v[160:161], v[146:147], v[10:11], v[160:161]
	ds_read_b128 v[144:147], v196 offset:3296
	v_pk_fma_f32 v[162:163], v[148:149], v[12:13], v[162:163]
	v_pk_fma_f32 v[164:165], v[150:151], v[14:15], v[164:165]
	ds_read_b128 v[148:151], v196 offset:3312
	v_pk_fma_f32 v[158:159], v[176:177], v[16:17], v[158:159]
	v_pk_fma_f32 v[160:161], v[178:179], v[18:19], v[160:161]
	ds_read_b128 v[176:179], v196 offset:4352
	v_pk_fma_f32 v[162:163], v[180:181], v[20:21], v[162:163]
	v_pk_fma_f32 v[164:165], v[182:183], v[22:23], v[164:165]
	ds_read_b128 v[180:183], v196 offset:4368
	v_pk_fma_f32 v[158:159], v[184:185], v[24:25], v[158:159]
	v_pk_fma_f32 v[160:161], v[186:187], v[26:27], v[160:161]
	ds_read_b128 v[184:187], v196 offset:4384
	v_pk_fma_f32 v[162:163], v[188:189], v[28:29], v[162:163]
	v_pk_fma_f32 v[164:165], v[190:191], v[30:31], v[164:165]
	ds_read_b128 v[188:191], v196 offset:4400
	v_pk_fma_f32 v[158:159], v[200:201], v[32:33], v[158:159]
	v_pk_fma_f32 v[160:161], v[202:203], v[34:35], v[160:161]
	ds_read_b128 v[200:203], v196 offset:4416
	v_pk_fma_f32 v[162:163], v[204:205], v[36:37], v[162:163]
	v_pk_fma_f32 v[164:165], v[206:207], v[38:39], v[164:165]
	ds_read_b128 v[204:207], v196 offset:4432
	v_pk_fma_f32 v[158:159], v[214:215], v[40:41], v[158:159]
	v_pk_fma_f32 v[160:161], v[216:217], v[42:43], v[160:161]
	ds_read_b128 v[214:217], v196 offset:4448
	v_pk_fma_f32 v[162:163], v[238:239], v[44:45], v[162:163]
	v_pk_fma_f32 v[164:165], v[240:241], v[46:47], v[164:165]
	ds_read_b128 v[238:241], v196 offset:4464
	s_waitcnt lgkmcnt(11)
	v_pk_fma_f32 v[158:159], v[136:137], v[48:49], v[158:159]
	v_pk_fma_f32 v[160:161], v[138:139], v[50:51], v[160:161]
	ds_read_b128 v[136:139], v196 offset:4480
	s_waitcnt lgkmcnt(11)
	v_pk_fma_f32 v[162:163], v[140:141], v[52:53], v[162:163]
	v_pk_fma_f32 v[164:165], v[142:143], v[54:55], v[164:165]
	ds_read_b128 v[140:143], v196 offset:4496
	s_waitcnt lgkmcnt(11)
	v_pk_fma_f32 v[158:159], v[144:145], v[56:57], v[158:159]
	v_pk_fma_f32 v[160:161], v[146:147], v[58:59], v[160:161]
	ds_read_b128 v[144:147], v196 offset:4512
	s_waitcnt lgkmcnt(11)
; #define LAS __attribute__((address_space(3)))
; template <int MODE> __device__ __forceinline__ void rwkv_item(const Params& P, int e, int c, int h, LAS float* slab, int lane) {
;     ...
;         for (int s = 0; s < SB; ++s) {
;             const LAS float* st = slab + s * 512;
;             f32x2 aS0 = {0.f, 0.f}, aS1 = {0.f, 0.f}, aC0 = {0.f, 0.f}, aC1 = {0.f, 0.f};
;             constexpr int DB = 4, UB = 2;
;             constexpr int NDB = 16 / DB, NUB = 16 / UB;
;             constexpr int NB = MODE == 1 ? 2 : 1;
;             f32x4 kd[NB][DB];
;             f32x4 wq[NB][UB], bq[NB][UB], kq[NB][UB], rq[NB][MODE == 1 ? UB : 1];
;     ...
;             if (NB == 2) RW_LD_DOT(0, 0);
;             const float v = st[320 + lane];
; #pragma unroll
;             for (int hb = 0; hb < NDB; ++hb) {
;                 if (NB == 2) { if (hb + 1 < NDB) RW_LD_DOT((hb + 1) & 1, hb + 1); else RW_LD_UPD(0, 0); } else RW_LD_DOT(0, hb);
;                 __builtin_amdgcn_sched_barrier(0);
; #pragma unroll
;                 for (int q = 0; q < DB; ++q) {
;                     const int qq = DB * hb + q; const f32x4 k4 = kd[hb & (NB - 1)][q];
;                     aS0 += S2[2 * qq] * (f32x2){k4.x, k4.y}; aS1 += S2[2 * qq + 1] * (f32x2){k4.z, k4.w};
;                     if (MODE == 0) { aC0 += C2[2 * qq] * (f32x2){k4.x, k4.y}; aC1 += C2[2 * qq + 1] * (f32x2){k4.z, k4.w}; }
;                 }
;                 __builtin_amdgcn_sched_barrier(0);
;             }
;             const float nsk = -((aS0.x + aS0.y) + (aS1.x + aS1.y));
;             const float nskC = -((aC0.x + aC0.y) + (aC1.x + aC1.y));
;             f32x2 y0 = {0.f, 0.f}, y1 = {0.f, 0.f};
; #pragma unroll
;             for (int qb = 0; qb < NUB; ++qb) {
;                 if (NB == 2) { if (qb + 1 < NUB) RW_LD_UPD((qb + 1) & 1, qb + 1); } else RW_LD_UPD(0, qb);
;                 __builtin_amdgcn_sched_barrier(0);
; #pragma unroll
;                 for (int q = 0; q < UB; ++q) {
;                     const int qq = UB * qb + q;
;                     const f32x4 w4 = wq[qb & (NB - 1)][q], b4 = bq[qb & (NB - 1)][q], k4 = kq[qb & (NB - 1)][q];
;                     if (MODE == 0) {
;                         S2[2 * qq] = S2[2 * qq] * (f32x2){w4.x, w4.y} + (f32x2){b4.x, b4.y} * nsk;
;                         S2[2 * qq + 1] = S2[2 * qq + 1] * (f32x2){w4.z, w4.w} + (f32x2){b4.z, b4.w} * nsk;
	v_pk_fma_f32 v[162:163], v[148:149], v[60:61], v[162:163]
	v_pk_fma_f32 v[164:165], v[150:151], v[62:63], v[164:165]
	ds_read_b128 v[148:151], v196 offset:4528
	v_pk_add_f32 v[158:159], v[158:159], v[162:163]
	v_pk_add_f32 v[160:161], v[160:161], v[164:165]
	v_add_f32_e32 v198, v158, v159
	v_add_f32_e32 v192, v160, v161
	v_add_f32_e32 v198, v192, v198
	ds_write_b32 v109, v198 offset:2048
	s_waitcnt lgkmcnt(10)
	ds_read_b32 v194, v109 offset:5376
	ds_read_b128 v[124:127], v199 offset:4608
	ds_read_b128 v[230:233], v199 offset:4864
	ds_read_b128 v[128:131], v199 offset:4624
	ds_read_b128 v[234:237], v199 offset:4880
	v_pk_fma_f32 v[158:159], v[0:1], v[176:177], 0 op_sel_hi:[1,1,0]
	v_pk_fma_f32 v[160:161], v[2:3], v[178:179], 0 op_sel_hi:[1,1,0]
	s_waitcnt lgkmcnt(14)
	ds_read_b128 v[176:179], v196 offset:4544
	v_pk_fma_f32 v[162:163], v[4:5], v[180:181], 0 op_sel_hi:[1,1,0]
	v_pk_fma_f32 v[164:165], v[6:7], v[182:183], 0 op_sel_hi:[1,1,0]
	s_waitcnt lgkmcnt(14)
	ds_read_b128 v[180:183], v196 offset:4560
	v_pk_fma_f32 v[158:159], v[8:9], v[184:185], v[158:159]
	v_pk_fma_f32 v[160:161], v[10:11], v[186:187], v[160:161]
	s_waitcnt lgkmcnt(14)
	ds_read_b128 v[184:187], v196 offset:4576
	v_pk_fma_f32 v[162:163], v[12:13], v[188:189], v[162:163]
	v_pk_fma_f32 v[164:165], v[14:15], v[190:191], v[164:165]
	s_waitcnt lgkmcnt(14)
	ds_read_b128 v[188:191], v196 offset:4592
	v_pk_fma_f32 v[158:159], v[16:17], v[200:201], v[158:159]
	v_pk_fma_f32 v[160:161], v[18:19], v[202:203], v[160:161]
	s_waitcnt lgkmcnt(14)
	ds_read_b128 v[200:203], v196 offset:5120
	v_pk_fma_f32 v[162:163], v[20:21], v[204:205], v[162:163]
	v_pk_fma_f32 v[164:165], v[22:23], v[206:207], v[164:165]
	s_waitcnt lgkmcnt(14)
	ds_read_b128 v[204:207], v196 offset:5136
	v_pk_fma_f32 v[158:159], v[24:25], v[214:215], v[158:159]
	v_pk_fma_f32 v[160:161], v[26:27], v[216:217], v[160:161]
	s_waitcnt lgkmcnt(14)
	ds_read_b128 v[214:217], v196 offset:5152
	v_pk_fma_f32 v[162:163], v[28:29], v[238:239], v[162:163]
	v_pk_fma_f32 v[164:165], v[30:31], v[240:241], v[164:165]
	s_waitcnt lgkmcnt(14)
	ds_read_b128 v[238:241], v196 offset:5168
	v_pk_fma_f32 v[158:159], v[32:33], v[136:137], v[158:159]
	v_pk_fma_f32 v[160:161], v[34:35], v[138:139], v[160:161]
	s_waitcnt lgkmcnt(14)
	ds_read_b128 v[136:139], v196 offset:5184
	v_pk_fma_f32 v[162:163], v[36:37], v[140:141], v[162:163]
	v_pk_fma_f32 v[164:165], v[38:39], v[142:143], v[164:165]
	s_waitcnt lgkmcnt(14)
	ds_read_b128 v[140:143], v196 offset:5200
	v_pk_fma_f32 v[158:159], v[40:41], v[144:145], v[158:159]
	v_pk_fma_f32 v[160:161], v[42:43], v[146:147], v[160:161]
	s_waitcnt lgkmcnt(14)
	ds_read_b128 v[144:147], v196 offset:5216
	v_pk_fma_f32 v[162:163], v[44:45], v[148:149], v[162:163]
	v_pk_fma_f32 v[164:165], v[46:47], v[150:151], v[164:165]
	s_waitcnt lgkmcnt(14)
	ds_read_b128 v[148:151], v196 offset:5232
	s_waitcnt lgkmcnt(11)
	v_pk_fma_f32 v[158:159], v[48:49], v[176:177], v[158:159]
	v_pk_fma_f32 v[160:161], v[50:51], v[178:179], v[160:161]
	ds_read_b128 v[176:179], v196 offset:5248
	s_waitcnt lgkmcnt(11)
	v_pk_fma_f32 v[162:163], v[52:53], v[180:181], v[162:163]
	v_pk_fma_f32 v[164:165], v[54:55], v[182:183], v[164:165]
	ds_read_b128 v[180:183], v196 offset:5264
	s_waitcnt lgkmcnt(11)
	v_pk_fma_f32 v[158:159], v[56:57], v[184:185], v[158:159]
	v_pk_fma_f32 v[160:161], v[58:59], v[186:187], v[160:161]
	ds_read_b128 v[184:187], v196 offset:5280
	s_waitcnt lgkmcnt(11)
	v_pk_fma_f32 v[162:163], v[60:61], v[188:189], v[162:163]
	v_pk_fma_f32 v[164:165], v[62:63], v[190:191], v[164:165]
	ds_read_b128 v[188:191], v196 offset:5296
	v_pk_add_f32 v[158:159], v[158:159], v[162:163]
	v_pk_add_f32 v[160:161], v[160:161], v[164:165]
	v_add_f32_e32 v192, v158, v159
	v_add_f32_e32 v198, v160, v161
	v_sub_f32_e64 v193, -v198, v192
	s_nop 1
	v_mfma_f32_4x4x1_16b_f32 v[0:3], v124, v193, v[0:3]
	v_mfma_f32_4x4x1_16b_f32 v[4:7], v125, v193, v[4:7]
	v_mfma_f32_4x4x1_16b_f32 v[0:3], v230, v194, v[0:3]
	v_mfma_f32_4x4x1_16b_f32 v[8:11], v126, v193, v[8:11]
	v_mfma_f32_4x4x1_16b_f32 v[4:7], v231, v194, v[4:7]
	v_mfma_f32_4x4x1_16b_f32 v[12:15], v127, v193, v[12:15]
	v_mfma_f32_4x4x1_16b_f32 v[8:11], v232, v194, v[8:11]
	ds_read_b128 v[124:127], v199 offset:4640
	v_mfma_f32_4x4x1_16b_f32 v[16:19], v128, v193, v[16:19]
	v_mfma_f32_4x4x1_16b_f32 v[12:15], v233, v194, v[12:15]
	ds_read_b128 v[230:233], v199 offset:4896
	v_mfma_f32_4x4x1_16b_f32 v[20:23], v129, v193, v[20:23]
	v_mfma_f32_4x4x1_16b_f32 v[16:19], v234, v194, v[16:19]
	v_mfma_f32_4x4x1_16b_f32 v[24:27], v130, v193, v[24:27]
	v_mfma_f32_4x4x1_16b_f32 v[20:23], v235, v194, v[20:23]
	v_mfma_f32_4x4x1_16b_f32 v[28:31], v131, v193, v[28:31]
	v_mfma_f32_4x4x1_16b_f32 v[24:27], v236, v194, v[24:27]
	ds_read_b128 v[128:131], v199 offset:4656
	s_waitcnt lgkmcnt(2)
	v_mfma_f32_4x4x1_16b_f32 v[32:35], v124, v193, v[32:35]
	v_mfma_f32_4x4x1_16b_f32 v[28:31], v237, v194, v[28:31]
	ds_read_b128 v[234:237], v199 offset:4912
	v_mfma_f32_4x4x1_16b_f32 v[36:39], v125, v193, v[36:39]
	s_waitcnt lgkmcnt(2)
	v_mfma_f32_4x4x1_16b_f32 v[32:35], v230, v194, v[32:35]
	v_mfma_f32_4x4x1_16b_f32 v[40:43], v126, v193, v[40:43]
	v_mfma_f32_4x4x1_16b_f32 v[36:39], v231, v194, v[36:39]
	v_mfma_f32_4x4x1_16b_f32 v[44:47], v127, v193, v[44:47]
	v_mfma_f32_4x4x1_16b_f32 v[40:43], v232, v194, v[40:43]
	s_waitcnt lgkmcnt(1)
	v_mfma_f32_4x4x1_16b_f32 v[48:51], v128, v193, v[48:51]
	v_mfma_f32_4x4x1_16b_f32 v[44:47], v233, v194, v[44:47]
	v_mfma_f32_4x4x1_16b_f32 v[52:55], v129, v193, v[52:55]
	s_waitcnt lgkmcnt(0)
; #define LAS __attribute__((address_space(3)))
; template <int MODE> __device__ __forceinline__ void rwkv_item(const Params& P, int e, int c, int h, LAS float* slab, int lane) {
;     ...
;         for (int s = 0; s < SB; ++s) {
;             const LAS float* st = slab + s * 512;
;             f32x2 aS0 = {0.f, 0.f}, aS1 = {0.f, 0.f}, aC0 = {0.f, 0.f}, aC1 = {0.f, 0.f};
;             constexpr int DB = 4, UB = 2;
;             constexpr int NDB = 16 / DB, NUB = 16 / UB;
;             constexpr int NB = MODE == 1 ? 2 : 1;
;             f32x4 kd[NB][DB];
;             f32x4 wq[NB][UB], bq[NB][UB], kq[NB][UB], rq[NB][MODE == 1 ? UB : 1];
;     ...
;             if (NB == 2) RW_LD_DOT(0, 0);
;             const float v = st[320 + lane];
; #pragma unroll
;             for (int hb = 0; hb < NDB; ++hb) {
;                 if (NB == 2) { if (hb + 1 < NDB) RW_LD_DOT((hb + 1) & 1, hb + 1); else RW_LD_UPD(0, 0); } else RW_LD_DOT(0, hb);
;                 __builtin_amdgcn_sched_barrier(0);
; #pragma unroll
;                 for (int q = 0; q < DB; ++q) {
;                     const int qq = DB * hb + q; const f32x4 k4 = kd[hb & (NB - 1)][q];
;                     aS0 += S2[2 * qq] * (f32x2){k4.x, k4.y}; aS1 += S2[2 * qq + 1] * (f32x2){k4.z, k4.w};
;                     if (MODE == 0) { aC0 += C2[2 * qq] * (f32x2){k4.x, k4.y}; aC1 += C2[2 * qq + 1] * (f32x2){k4.z, k4.w}; }
;                 }
;                 __builtin_amdgcn_sched_barrier(0);
;             }
;             const float nsk = -((aS0.x + aS0.y) + (aS1.x + aS1.y));
;             const float nskC = -((aC0.x + aC0.y) + (aC1.x + aC1.y));
;             f32x2 y0 = {0.f, 0.f}, y1 = {0.f, 0.f};
; #pragma unroll
;             for (int qb = 0; qb < NUB; ++qb) {
;                 if (NB == 2) { if (qb + 1 < NUB) RW_LD_UPD((qb + 1) & 1, qb + 1); } else RW_LD_UPD(0, qb);
;                 __builtin_amdgcn_sched_barrier(0);
; #pragma unroll
;                 for (int q = 0; q < UB; ++q) {
;                     const int qq = UB * qb + q;
;                     const f32x4 w4 = wq[qb & (NB - 1)][q], b4 = bq[qb & (NB - 1)][q], k4 = kq[qb & (NB - 1)][q];
;                     if (MODE == 0) {
;                         S2[2 * qq] = S2[2 * qq] * (f32x2){w4.x, w4.y} + (f32x2){b4.x, b4.y} * nsk;
;                         S2[2 * qq + 1] = S2[2 * qq + 1] * (f32x2){w4.z, w4.w} + (f32x2){b4.z, b4.w} * nsk;
	v_mfma_f32_4x4x1_16b_f32 v[48:51], v234, v194, v[48:51]
	v_mfma_f32_4x4x1_16b_f32 v[56:59], v130, v193, v[56:59]
	v_mfma_f32_4x4x1_16b_f32 v[52:55], v235, v194, v[52:55]
	v_mfma_f32_4x4x1_16b_f32 v[60:63], v131, v193, v[60:63]
	v_mfma_f32_4x4x1_16b_f32 v[56:59], v236, v194, v[56:59]
	s_nop 0
	v_mfma_f32_4x4x1_16b_f32 v[60:63], v237, v194, v[60:63]
	v_pk_fma_f32 v[158:159], v[200:201], v[0:1], 0 op_sel_hi:[1,1,0]
	v_pk_fma_f32 v[160:161], v[202:203], v[2:3], 0 op_sel_hi:[1,1,0]
	ds_read_b128 v[200:203], v196 offset:5312
	v_pk_fma_f32 v[162:163], v[204:205], v[4:5], 0 op_sel_hi:[1,1,0]
	v_pk_fma_f32 v[164:165], v[206:207], v[6:7], 0 op_sel_hi:[1,1,0]
	ds_read_b128 v[204:207], v196 offset:5328
	v_pk_fma_f32 v[158:159], v[214:215], v[8:9], v[158:159]
	v_pk_fma_f32 v[160:161], v[216:217], v[10:11], v[160:161]
	ds_read_b128 v[214:217], v196 offset:5344
	v_pk_fma_f32 v[162:163], v[238:239], v[12:13], v[162:163]
	v_pk_fma_f32 v[164:165], v[240:241], v[14:15], v[164:165]
	ds_read_b128 v[238:241], v196 offset:5360
	v_pk_fma_f32 v[158:159], v[136:137], v[16:17], v[158:159]
	v_pk_fma_f32 v[160:161], v[138:139], v[18:19], v[160:161]
	ds_read_b128 v[136:139], v196 offset:6400
	v_pk_fma_f32 v[162:163], v[140:141], v[20:21], v[162:163]
	v_pk_fma_f32 v[164:165], v[142:143], v[22:23], v[164:165]
	ds_read_b128 v[140:143], v196 offset:6416
	v_pk_fma_f32 v[158:159], v[144:145], v[24:25], v[158:159]
	v_pk_fma_f32 v[160:161], v[146:147], v[26:27], v[160:161]
	ds_read_b128 v[144:147], v196 offset:6432
	v_pk_fma_f32 v[162:163], v[148:149], v[28:29], v[162:163]
	v_pk_fma_f32 v[164:165], v[150:151], v[30:31], v[164:165]
	ds_read_b128 v[148:151], v196 offset:6448
	v_pk_fma_f32 v[158:159], v[176:177], v[32:33], v[158:159]
	v_pk_fma_f32 v[160:161], v[178:179], v[34:35], v[160:161]
	ds_read_b128 v[176:179], v196 offset:6464
	v_pk_fma_f32 v[162:163], v[180:181], v[36:37], v[162:163]
	v_pk_fma_f32 v[164:165], v[182:183], v[38:39], v[164:165]
	ds_read_b128 v[180:183], v196 offset:6480
	v_pk_fma_f32 v[158:159], v[184:185], v[40:41], v[158:159]
	v_pk_fma_f32 v[160:161], v[186:187], v[42:43], v[160:161]
	ds_read_b128 v[184:187], v196 offset:6496
	v_pk_fma_f32 v[162:163], v[188:189], v[44:45], v[162:163]
	v_pk_fma_f32 v[164:165], v[190:191], v[46:47], v[164:165]
	ds_read_b128 v[188:191], v196 offset:6512
	s_waitcnt lgkmcnt(11)
	v_pk_fma_f32 v[158:159], v[200:201], v[48:49], v[158:159]
	v_pk_fma_f32 v[160:161], v[202:203], v[50:51], v[160:161]
	ds_read_b128 v[200:203], v196 offset:6528
	s_waitcnt lgkmcnt(11)
	v_pk_fma_f32 v[162:163], v[204:205], v[52:53], v[162:163]
	v_pk_fma_f32 v[164:165], v[206:207], v[54:55], v[164:165]
	ds_read_b128 v[204:207], v196 offset:6544
	s_waitcnt lgkmcnt(11)
	v_pk_fma_f32 v[158:159], v[214:215], v[56:57], v[158:159]
	v_pk_fma_f32 v[160:161], v[216:217], v[58:59], v[160:161]
	ds_read_b128 v[214:217], v196 offset:6560
	s_waitcnt lgkmcnt(11)
	v_pk_fma_f32 v[162:163], v[238:239], v[60:61], v[162:163]
	v_pk_fma_f32 v[164:165], v[240:241], v[62:63], v[164:165]
	ds_read_b128 v[238:241], v196 offset:6576
	v_pk_add_f32 v[158:159], v[158:159], v[162:163]
	v_pk_add_f32 v[160:161], v[160:161], v[164:165]
	v_add_f32_e32 v198, v158, v159
	v_add_f32_e32 v192, v160, v161
	v_add_f32_e32 v198, v192, v198
	ds_write_b32 v109, v198 offset:4096
	s_waitcnt lgkmcnt(10)
	ds_read_b32 v194, v109 offset:7424
	ds_read_b128 v[124:127], v199 offset:6656
	ds_read_b128 v[230:233], v199 offset:6912
	ds_read_b128 v[128:131], v199 offset:6672
	ds_read_b128 v[234:237], v199 offset:6928
	v_pk_fma_f32 v[158:159], v[0:1], v[136:137], 0 op_sel_hi:[1,1,0]
	v_pk_fma_f32 v[160:161], v[2:3], v[138:139], 0 op_sel_hi:[1,1,0]
	s_waitcnt lgkmcnt(14)
	ds_read_b128 v[136:139], v196 offset:6592
	v_pk_fma_f32 v[162:163], v[4:5], v[140:141], 0 op_sel_hi:[1,1,0]
	v_pk_fma_f32 v[164:165], v[6:7], v[142:143], 0 op_sel_hi:[1,1,0]
	s_waitcnt lgkmcnt(14)
	ds_read_b128 v[140:143], v196 offset:6608
	v_pk_fma_f32 v[158:159], v[8:9], v[144:145], v[158:159]
	v_pk_fma_f32 v[160:161], v[10:11], v[146:147], v[160:161]
	s_waitcnt lgkmcnt(14)
	ds_read_b128 v[144:147], v196 offset:6624
	v_pk_fma_f32 v[162:163], v[12:13], v[148:149], v[162:163]
	v_pk_fma_f32 v[164:165], v[14:15], v[150:151], v[164:165]
	s_waitcnt lgkmcnt(14)
	ds_read_b128 v[148:151], v196 offset:6640
	v_pk_fma_f32 v[158:159], v[16:17], v[176:177], v[158:159]
	v_pk_fma_f32 v[160:161], v[18:19], v[178:179], v[160:161]
	s_waitcnt lgkmcnt(14)
	ds_read_b128 v[176:179], v196 offset:7168
	v_pk_fma_f32 v[162:163], v[20:21], v[180:181], v[162:163]
	v_pk_fma_f32 v[164:165], v[22:23], v[182:183], v[164:165]
	s_waitcnt lgkmcnt(14)
	ds_read_b128 v[180:183], v196 offset:7184
	v_pk_fma_f32 v[158:159], v[24:25], v[184:185], v[158:159]
	v_pk_fma_f32 v[160:161], v[26:27], v[186:187], v[160:161]
	s_waitcnt lgkmcnt(14)
	ds_read_b128 v[184:187], v196 offset:7200
	v_pk_fma_f32 v[162:163], v[28:29], v[188:189], v[162:163]
	v_pk_fma_f32 v[164:165], v[30:31], v[190:191], v[164:165]
	s_waitcnt lgkmcnt(14)
	ds_read_b128 v[188:191], v196 offset:7216
	v_pk_fma_f32 v[158:159], v[32:33], v[200:201], v[158:159]
	v_pk_fma_f32 v[160:161], v[34:35], v[202:203], v[160:161]
	s_waitcnt lgkmcnt(14)
	ds_read_b128 v[200:203], v196 offset:7232
	v_pk_fma_f32 v[162:163], v[36:37], v[204:205], v[162:163]
	v_pk_fma_f32 v[164:165], v[38:39], v[206:207], v[164:165]
	s_waitcnt lgkmcnt(14)
	ds_read_b128 v[204:207], v196 offset:7248
	v_pk_fma_f32 v[158:159], v[40:41], v[214:215], v[158:159]
	v_pk_fma_f32 v[160:161], v[42:43], v[216:217], v[160:161]
	s_waitcnt lgkmcnt(14)
	ds_read_b128 v[214:217], v196 offset:7264
	v_pk_fma_f32 v[162:163], v[44:45], v[238:239], v[162:163]
	v_pk_fma_f32 v[164:165], v[46:47], v[240:241], v[164:165]
	s_waitcnt lgkmcnt(14)
; #define LAS __attribute__((address_space(3)))
; template <int MODE> __device__ __forceinline__ void rwkv_item(const Params& P, int e, int c, int h, LAS float* slab, int lane) {
;     ...
;         for (int s = 0; s < SB; ++s) {
;             const LAS float* st = slab + s * 512;
;             f32x2 aS0 = {0.f, 0.f}, aS1 = {0.f, 0.f}, aC0 = {0.f, 0.f}, aC1 = {0.f, 0.f};
;             constexpr int DB = 4, UB = 2;
;             constexpr int NDB = 16 / DB, NUB = 16 / UB;
;             constexpr int NB = MODE == 1 ? 2 : 1;
;             f32x4 kd[NB][DB];
;             f32x4 wq[NB][UB], bq[NB][UB], kq[NB][UB], rq[NB][MODE == 1 ? UB : 1];
;     ...
;             if (NB == 2) RW_LD_DOT(0, 0);
;             const float v = st[320 + lane];
; #pragma unroll
;             for (int hb = 0; hb < NDB; ++hb) {
;                 if (NB == 2) { if (hb + 1 < NDB) RW_LD_DOT((hb + 1) & 1, hb + 1); else RW_LD_UPD(0, 0); } else RW_LD_DOT(0, hb);
;                 __builtin_amdgcn_sched_barrier(0);
; #pragma unroll
;                 for (int q = 0; q < DB; ++q) {
;                     const int qq = DB * hb + q; const f32x4 k4 = kd[hb & (NB - 1)][q];
;                     aS0 += S2[2 * qq] * (f32x2){k4.x, k4.y}; aS1 += S2[2 * qq + 1] * (f32x2){k4.z, k4.w};
;                     if (MODE == 0) { aC0 += C2[2 * qq] * (f32x2){k4.x, k4.y}; aC1 += C2[2 * qq + 1] * (f32x2){k4.z, k4.w}; }
;                 }
;                 __builtin_amdgcn_sched_barrier(0);
;             }
;             const float nsk = -((aS0.x + aS0.y) + (aS1.x + aS1.y));
;             const float nskC = -((aC0.x + aC0.y) + (aC1.x + aC1.y));
;             f32x2 y0 = {0.f, 0.f}, y1 = {0.f, 0.f};
; #pragma unroll
;             for (int qb = 0; qb < NUB; ++qb) {
;                 if (NB == 2) { if (qb + 1 < NUB) RW_LD_UPD((qb + 1) & 1, qb + 1); } else RW_LD_UPD(0, qb);
;                 __builtin_amdgcn_sched_barrier(0);
; #pragma unroll
;                 for (int q = 0; q < UB; ++q) {
;                     const int qq = UB * qb + q;
;                     const f32x4 w4 = wq[qb & (NB - 1)][q], b4 = bq[qb & (NB - 1)][q], k4 = kq[qb & (NB - 1)][q];
;                     if (MODE == 0) {
;                         S2[2 * qq] = S2[2 * qq] * (f32x2){w4.x, w4.y} + (f32x2){b4.x, b4.y} * nsk;
;                         S2[2 * qq + 1] = S2[2 * qq + 1] * (f32x2){w4.z, w4.w} + (f32x2){b4.z, b4.w} * nsk;
	ds_read_b128 v[238:241], v196 offset:7280
	s_waitcnt lgkmcnt(11)
	v_pk_fma_f32 v[158:159], v[48:49], v[136:137], v[158:159]
	v_pk_fma_f32 v[160:161], v[50:51], v[138:139], v[160:161]
	ds_read_b128 v[136:139], v196 offset:7296
	s_waitcnt lgkmcnt(11)
	v_pk_fma_f32 v[162:163], v[52:53], v[140:141], v[162:163]
	v_pk_fma_f32 v[164:165], v[54:55], v[142:143], v[164:165]
	ds_read_b128 v[140:143], v196 offset:7312
	s_waitcnt lgkmcnt(11)
	v_pk_fma_f32 v[158:159], v[56:57], v[144:145], v[158:159]
	v_pk_fma_f32 v[160:161], v[58:59], v[146:147], v[160:161]
	ds_read_b128 v[144:147], v196 offset:7328
	s_waitcnt lgkmcnt(11)
	v_pk_fma_f32 v[162:163], v[60:61], v[148:149], v[162:163]
	v_pk_fma_f32 v[164:165], v[62:63], v[150:151], v[164:165]
	ds_read_b128 v[148:151], v196 offset:7344
	v_pk_add_f32 v[158:159], v[158:159], v[162:163]
	v_pk_add_f32 v[160:161], v[160:161], v[164:165]
	v_add_f32_e32 v192, v158, v159
	v_add_f32_e32 v198, v160, v161
	v_sub_f32_e64 v193, -v198, v192
	s_nop 1
	v_mfma_f32_4x4x1_16b_f32 v[0:3], v124, v193, v[0:3]
	v_mfma_f32_4x4x1_16b_f32 v[4:7], v125, v193, v[4:7]
	v_mfma_f32_4x4x1_16b_f32 v[0:3], v230, v194, v[0:3]
	v_mfma_f32_4x4x1_16b_f32 v[8:11], v126, v193, v[8:11]
	v_mfma_f32_4x4x1_16b_f32 v[4:7], v231, v194, v[4:7]
	v_mfma_f32_4x4x1_16b_f32 v[12:15], v127, v193, v[12:15]
	v_mfma_f32_4x4x1_16b_f32 v[8:11], v232, v194, v[8:11]
	ds_read_b128 v[124:127], v199 offset:6688
	v_mfma_f32_4x4x1_16b_f32 v[16:19], v128, v193, v[16:19]
	v_mfma_f32_4x4x1_16b_f32 v[12:15], v233, v194, v[12:15]
	ds_read_b128 v[230:233], v199 offset:6944
	v_mfma_f32_4x4x1_16b_f32 v[20:23], v129, v193, v[20:23]
	v_mfma_f32_4x4x1_16b_f32 v[16:19], v234, v194, v[16:19]
	v_mfma_f32_4x4x1_16b_f32 v[24:27], v130, v193, v[24:27]
	v_mfma_f32_4x4x1_16b_f32 v[20:23], v235, v194, v[20:23]
	v_mfma_f32_4x4x1_16b_f32 v[28:31], v131, v193, v[28:31]
	v_mfma_f32_4x4x1_16b_f32 v[24:27], v236, v194, v[24:27]
	ds_read_b128 v[128:131], v199 offset:6704
	s_waitcnt lgkmcnt(2)
	v_mfma_f32_4x4x1_16b_f32 v[32:35], v124, v193, v[32:35]
	v_mfma_f32_4x4x1_16b_f32 v[28:31], v237, v194, v[28:31]
	ds_read_b128 v[234:237], v199 offset:6960
	v_mfma_f32_4x4x1_16b_f32 v[36:39], v125, v193, v[36:39]
	s_waitcnt lgkmcnt(2)
	v_mfma_f32_4x4x1_16b_f32 v[32:35], v230, v194, v[32:35]
	v_mfma_f32_4x4x1_16b_f32 v[40:43], v126, v193, v[40:43]
	v_mfma_f32_4x4x1_16b_f32 v[36:39], v231, v194, v[36:39]
	v_mfma_f32_4x4x1_16b_f32 v[44:47], v127, v193, v[44:47]
	v_mfma_f32_4x4x1_16b_f32 v[40:43], v232, v194, v[40:43]
	s_waitcnt lgkmcnt(1)
	v_mfma_f32_4x4x1_16b_f32 v[48:51], v128, v193, v[48:51]
	v_mfma_f32_4x4x1_16b_f32 v[44:47], v233, v194, v[44:47]
	v_mfma_f32_4x4x1_16b_f32 v[52:55], v129, v193, v[52:55]
	s_waitcnt lgkmcnt(0)
	v_mfma_f32_4x4x1_16b_f32 v[48:51], v234, v194, v[48:51]
	v_mfma_f32_4x4x1_16b_f32 v[56:59], v130, v193, v[56:59]
	v_mfma_f32_4x4x1_16b_f32 v[52:55], v235, v194, v[52:55]
	v_mfma_f32_4x4x1_16b_f32 v[60:63], v131, v193, v[60:63]
	v_mfma_f32_4x4x1_16b_f32 v[56:59], v236, v194, v[56:59]
	s_nop 0
	v_mfma_f32_4x4x1_16b_f32 v[60:63], v237, v194, v[60:63]
	v_pk_fma_f32 v[158:159], v[176:177], v[0:1], 0 op_sel_hi:[1,1,0]
	v_pk_fma_f32 v[160:161], v[178:179], v[2:3], 0 op_sel_hi:[1,1,0]
	ds_read_b128 v[176:179], v196 offset:7360
	v_pk_fma_f32 v[162:163], v[180:181], v[4:5], 0 op_sel_hi:[1,1,0]
	v_pk_fma_f32 v[164:165], v[182:183], v[6:7], 0 op_sel_hi:[1,1,0]
	ds_read_b128 v[180:183], v196 offset:7376
	v_pk_fma_f32 v[158:159], v[184:185], v[8:9], v[158:159]
	v_pk_fma_f32 v[160:161], v[186:187], v[10:11], v[160:161]
	ds_read_b128 v[184:187], v196 offset:7392
	v_pk_fma_f32 v[162:163], v[188:189], v[12:13], v[162:163]
	v_pk_fma_f32 v[164:165], v[190:191], v[14:15], v[164:165]
	ds_read_b128 v[188:191], v196 offset:7408
	v_pk_fma_f32 v[158:159], v[200:201], v[16:17], v[158:159]
	v_pk_fma_f32 v[160:161], v[202:203], v[18:19], v[160:161]
	ds_read_b128 v[200:203], v196 offset:8448
	v_pk_fma_f32 v[162:163], v[204:205], v[20:21], v[162:163]
	v_pk_fma_f32 v[164:165], v[206:207], v[22:23], v[164:165]
	ds_read_b128 v[204:207], v196 offset:8464
	v_pk_fma_f32 v[158:159], v[214:215], v[24:25], v[158:159]
	v_pk_fma_f32 v[160:161], v[216:217], v[26:27], v[160:161]
	ds_read_b128 v[214:217], v196 offset:8480
	v_pk_fma_f32 v[162:163], v[238:239], v[28:29], v[162:163]
	v_pk_fma_f32 v[164:165], v[240:241], v[30:31], v[164:165]
	ds_read_b128 v[238:241], v196 offset:8496
	v_pk_fma_f32 v[158:159], v[136:137], v[32:33], v[158:159]
	v_pk_fma_f32 v[160:161], v[138:139], v[34:35], v[160:161]
	ds_read_b128 v[136:139], v196 offset:8512
	v_pk_fma_f32 v[162:163], v[140:141], v[36:37], v[162:163]
	v_pk_fma_f32 v[164:165], v[142:143], v[38:39], v[164:165]
	ds_read_b128 v[140:143], v196 offset:8528
	v_pk_fma_f32 v[158:159], v[144:145], v[40:41], v[158:159]
	v_pk_fma_f32 v[160:161], v[146:147], v[42:43], v[160:161]
	ds_read_b128 v[144:147], v196 offset:8544
	v_pk_fma_f32 v[162:163], v[148:149], v[44:45], v[162:163]
	v_pk_fma_f32 v[164:165], v[150:151], v[46:47], v[164:165]
	ds_read_b128 v[148:151], v196 offset:8560
	s_waitcnt lgkmcnt(11)
	v_pk_fma_f32 v[158:159], v[176:177], v[48:49], v[158:159]
	v_pk_fma_f32 v[160:161], v[178:179], v[50:51], v[160:161]
	ds_read_b128 v[176:179], v196 offset:8576
	s_waitcnt lgkmcnt(11)
	v_pk_fma_f32 v[162:163], v[180:181], v[52:53], v[162:163]
	v_pk_fma_f32 v[164:165], v[182:183], v[54:55], v[164:165]
	ds_read_b128 v[180:183], v196 offset:8592
	s_waitcnt lgkmcnt(11)
	v_pk_fma_f32 v[158:159], v[184:185], v[56:57], v[158:159]
	v_pk_fma_f32 v[160:161], v[186:187], v[58:59], v[160:161]
	ds_read_b128 v[184:187], v196 offset:8608
	s_waitcnt lgkmcnt(11)
; #define LAS __attribute__((address_space(3)))
; template <int MODE> __device__ __forceinline__ void rwkv_item(const Params& P, int e, int c, int h, LAS float* slab, int lane) {
;     ...
;         for (int s = 0; s < SB; ++s) {
;             const LAS float* st = slab + s * 512;
;             f32x2 aS0 = {0.f, 0.f}, aS1 = {0.f, 0.f}, aC0 = {0.f, 0.f}, aC1 = {0.f, 0.f};
;             constexpr int DB = 4, UB = 2;
;             constexpr int NDB = 16 / DB, NUB = 16 / UB;
;             constexpr int NB = MODE == 1 ? 2 : 1;
;             f32x4 kd[NB][DB];
;             f32x4 wq[NB][UB], bq[NB][UB], kq[NB][UB], rq[NB][MODE == 1 ? UB : 1];
;     ...
;             if (NB == 2) RW_LD_DOT(0, 0);
;             const float v = st[320 + lane];
; #pragma unroll
;             for (int hb = 0; hb < NDB; ++hb) {
;                 if (NB == 2) { if (hb + 1 < NDB) RW_LD_DOT((hb + 1) & 1, hb + 1); else RW_LD_UPD(0, 0); } else RW_LD_DOT(0, hb);
;                 __builtin_amdgcn_sched_barrier(0);
; #pragma unroll
;                 for (int q = 0; q < DB; ++q) {
;                     const int qq = DB * hb + q; const f32x4 k4 = kd[hb & (NB - 1)][q];
;                     aS0 += S2[2 * qq] * (f32x2){k4.x, k4.y}; aS1 += S2[2 * qq + 1] * (f32x2){k4.z, k4.w};
;                     if (MODE == 0) { aC0 += C2[2 * qq] * (f32x2){k4.x, k4.y}; aC1 += C2[2 * qq + 1] * (f32x2){k4.z, k4.w}; }
;                 }
;                 __builtin_amdgcn_sched_barrier(0);
;             }
;             const float nsk = -((aS0.x + aS0.y) + (aS1.x + aS1.y));
;             const float nskC = -((aC0.x + aC0.y) + (aC1.x + aC1.y));
;             f32x2 y0 = {0.f, 0.f}, y1 = {0.f, 0.f};
; #pragma unroll
;             for (int qb = 0; qb < NUB; ++qb) {
;                 if (NB == 2) { if (qb + 1 < NUB) RW_LD_UPD((qb + 1) & 1, qb + 1); } else RW_LD_UPD(0, qb);
;                 __builtin_amdgcn_sched_barrier(0);
; #pragma unroll
;                 for (int q = 0; q < UB; ++q) {
;                     const int qq = UB * qb + q;
;                     const f32x4 w4 = wq[qb & (NB - 1)][q], b4 = bq[qb & (NB - 1)][q], k4 = kq[qb & (NB - 1)][q];
;                     if (MODE == 0) {
;                         S2[2 * qq] = S2[2 * qq] * (f32x2){w4.x, w4.y} + (f32x2){b4.x, b4.y} * nsk;
;                         S2[2 * qq + 1] = S2[2 * qq + 1] * (f32x2){w4.z, w4.w} + (f32x2){b4.z, b4.w} * nsk;
	v_pk_fma_f32 v[162:163], v[188:189], v[60:61], v[162:163]
	v_pk_fma_f32 v[164:165], v[190:191], v[62:63], v[164:165]
	ds_read_b128 v[188:191], v196 offset:8624
	v_pk_add_f32 v[158:159], v[158:159], v[162:163]
	v_pk_add_f32 v[160:161], v[160:161], v[164:165]
	v_add_f32_e32 v198, v158, v159
	v_add_f32_e32 v192, v160, v161
	v_add_f32_e32 v198, v192, v198
	ds_write_b32 v109, v198 offset:6144
	s_waitcnt lgkmcnt(10)
	ds_read_b32 v194, v109 offset:9472
	ds_read_b128 v[124:127], v199 offset:8704
	ds_read_b128 v[230:233], v199 offset:8960
	ds_read_b128 v[128:131], v199 offset:8720
	ds_read_b128 v[234:237], v199 offset:8976
	v_pk_fma_f32 v[158:159], v[0:1], v[200:201], 0 op_sel_hi:[1,1,0]
	v_pk_fma_f32 v[160:161], v[2:3], v[202:203], 0 op_sel_hi:[1,1,0]
	s_waitcnt lgkmcnt(14)
	ds_read_b128 v[200:203], v196 offset:8640
	v_pk_fma_f32 v[162:163], v[4:5], v[204:205], 0 op_sel_hi:[1,1,0]
	v_pk_fma_f32 v[164:165], v[6:7], v[206:207], 0 op_sel_hi:[1,1,0]
	s_waitcnt lgkmcnt(14)
	ds_read_b128 v[204:207], v196 offset:8656
	v_pk_fma_f32 v[158:159], v[8:9], v[214:215], v[158:159]
	v_pk_fma_f32 v[160:161], v[10:11], v[216:217], v[160:161]
	s_waitcnt lgkmcnt(14)
	ds_read_b128 v[214:217], v196 offset:8672
	v_pk_fma_f32 v[162:163], v[12:13], v[238:239], v[162:163]
	v_pk_fma_f32 v[164:165], v[14:15], v[240:241], v[164:165]
	s_waitcnt lgkmcnt(14)
	ds_read_b128 v[238:241], v196 offset:8688
	v_pk_fma_f32 v[158:159], v[16:17], v[136:137], v[158:159]
	v_pk_fma_f32 v[160:161], v[18:19], v[138:139], v[160:161]
	s_waitcnt lgkmcnt(14)
	ds_read_b128 v[136:139], v196 offset:9216
	v_pk_fma_f32 v[162:163], v[20:21], v[140:141], v[162:163]
	v_pk_fma_f32 v[164:165], v[22:23], v[142:143], v[164:165]
	s_waitcnt lgkmcnt(14)
	ds_read_b128 v[140:143], v196 offset:9232
	v_pk_fma_f32 v[158:159], v[24:25], v[144:145], v[158:159]
	v_pk_fma_f32 v[160:161], v[26:27], v[146:147], v[160:161]
	s_waitcnt lgkmcnt(14)
	ds_read_b128 v[144:147], v196 offset:9248
	v_pk_fma_f32 v[162:163], v[28:29], v[148:149], v[162:163]
	v_pk_fma_f32 v[164:165], v[30:31], v[150:151], v[164:165]
	s_waitcnt lgkmcnt(14)
	ds_read_b128 v[148:151], v196 offset:9264
	v_pk_fma_f32 v[158:159], v[32:33], v[176:177], v[158:159]
	v_pk_fma_f32 v[160:161], v[34:35], v[178:179], v[160:161]
	s_waitcnt lgkmcnt(14)
	ds_read_b128 v[176:179], v196 offset:9280
	v_pk_fma_f32 v[162:163], v[36:37], v[180:181], v[162:163]
	v_pk_fma_f32 v[164:165], v[38:39], v[182:183], v[164:165]
	s_waitcnt lgkmcnt(14)
	ds_read_b128 v[180:183], v196 offset:9296
	v_pk_fma_f32 v[158:159], v[40:41], v[184:185], v[158:159]
	v_pk_fma_f32 v[160:161], v[42:43], v[186:187], v[160:161]
	s_waitcnt lgkmcnt(14)
	ds_read_b128 v[184:187], v196 offset:9312
	v_pk_fma_f32 v[162:163], v[44:45], v[188:189], v[162:163]
	v_pk_fma_f32 v[164:165], v[46:47], v[190:191], v[164:165]
	s_waitcnt lgkmcnt(14)
	ds_read_b128 v[188:191], v196 offset:9328
	s_waitcnt lgkmcnt(11)
	v_pk_fma_f32 v[158:159], v[48:49], v[200:201], v[158:159]
	v_pk_fma_f32 v[160:161], v[50:51], v[202:203], v[160:161]
	ds_read_b128 v[200:203], v196 offset:9344
	s_waitcnt lgkmcnt(11)
	v_pk_fma_f32 v[162:163], v[52:53], v[204:205], v[162:163]
	v_pk_fma_f32 v[164:165], v[54:55], v[206:207], v[164:165]
	ds_read_b128 v[204:207], v196 offset:9360
	s_waitcnt lgkmcnt(11)
	v_pk_fma_f32 v[158:159], v[56:57], v[214:215], v[158:159]
	v_pk_fma_f32 v[160:161], v[58:59], v[216:217], v[160:161]
	ds_read_b128 v[214:217], v196 offset:9376
	s_waitcnt lgkmcnt(11)
	v_pk_fma_f32 v[162:163], v[60:61], v[238:239], v[162:163]
	v_pk_fma_f32 v[164:165], v[62:63], v[240:241], v[164:165]
	ds_read_b128 v[238:241], v196 offset:9392
	v_pk_add_f32 v[158:159], v[158:159], v[162:163]
	v_pk_add_f32 v[160:161], v[160:161], v[164:165]
	v_add_f32_e32 v192, v158, v159
	v_add_f32_e32 v198, v160, v161
	v_sub_f32_e64 v193, -v198, v192
	s_nop 1
	v_mfma_f32_4x4x1_16b_f32 v[0:3], v124, v193, v[0:3]
	v_mfma_f32_4x4x1_16b_f32 v[4:7], v125, v193, v[4:7]
	v_mfma_f32_4x4x1_16b_f32 v[0:3], v230, v194, v[0:3]
	v_mfma_f32_4x4x1_16b_f32 v[8:11], v126, v193, v[8:11]
	v_mfma_f32_4x4x1_16b_f32 v[4:7], v231, v194, v[4:7]
	v_mfma_f32_4x4x1_16b_f32 v[12:15], v127, v193, v[12:15]
	v_mfma_f32_4x4x1_16b_f32 v[8:11], v232, v194, v[8:11]
	ds_read_b128 v[124:127], v199 offset:8736
	v_mfma_f32_4x4x1_16b_f32 v[16:19], v128, v193, v[16:19]
	v_mfma_f32_4x4x1_16b_f32 v[12:15], v233, v194, v[12:15]
	ds_read_b128 v[230:233], v199 offset:8992
	v_mfma_f32_4x4x1_16b_f32 v[20:23], v129, v193, v[20:23]
	v_mfma_f32_4x4x1_16b_f32 v[16:19], v234, v194, v[16:19]
	v_mfma_f32_4x4x1_16b_f32 v[24:27], v130, v193, v[24:27]
	v_mfma_f32_4x4x1_16b_f32 v[20:23], v235, v194, v[20:23]
	v_mfma_f32_4x4x1_16b_f32 v[28:31], v131, v193, v[28:31]
	v_mfma_f32_4x4x1_16b_f32 v[24:27], v236, v194, v[24:27]
	ds_read_b128 v[128:131], v199 offset:8752
	s_waitcnt lgkmcnt(2)
	v_mfma_f32_4x4x1_16b_f32 v[32:35], v124, v193, v[32:35]
	v_mfma_f32_4x4x1_16b_f32 v[28:31], v237, v194, v[28:31]
	ds_read_b128 v[234:237], v199 offset:9008
	v_mfma_f32_4x4x1_16b_f32 v[36:39], v125, v193, v[36:39]
	s_waitcnt lgkmcnt(2)
	v_mfma_f32_4x4x1_16b_f32 v[32:35], v230, v194, v[32:35]
	v_mfma_f32_4x4x1_16b_f32 v[40:43], v126, v193, v[40:43]
	v_mfma_f32_4x4x1_16b_f32 v[36:39], v231, v194, v[36:39]
	v_mfma_f32_4x4x1_16b_f32 v[44:47], v127, v193, v[44:47]
	v_mfma_f32_4x4x1_16b_f32 v[40:43], v232, v194, v[40:43]
	s_waitcnt lgkmcnt(1)
	v_mfma_f32_4x4x1_16b_f32 v[48:51], v128, v193, v[48:51]
	v_mfma_f32_4x4x1_16b_f32 v[44:47], v233, v194, v[44:47]
	v_mfma_f32_4x4x1_16b_f32 v[52:55], v129, v193, v[52:55]
	s_waitcnt lgkmcnt(0)
; #define LAS __attribute__((address_space(3)))
; template <int MODE> __device__ __forceinline__ void rwkv_item(const Params& P, int e, int c, int h, LAS float* slab, int lane) {
;     ...
;         for (int s = 0; s < SB; ++s) {
;             const LAS float* st = slab + s * 512;
;             f32x2 aS0 = {0.f, 0.f}, aS1 = {0.f, 0.f}, aC0 = {0.f, 0.f}, aC1 = {0.f, 0.f};
;             constexpr int DB = 4, UB = 2;
;             constexpr int NDB = 16 / DB, NUB = 16 / UB;
;             constexpr int NB = MODE == 1 ? 2 : 1;
;             f32x4 kd[NB][DB];
;             f32x4 wq[NB][UB], bq[NB][UB], kq[NB][UB], rq[NB][MODE == 1 ? UB : 1];
;     ...
;             if (NB == 2) RW_LD_DOT(0, 0);
;             const float v = st[320 + lane];
; #pragma unroll
;             for (int hb = 0; hb < NDB; ++hb) {
;                 if (NB == 2) { if (hb + 1 < NDB) RW_LD_DOT((hb + 1) & 1, hb + 1); else RW_LD_UPD(0, 0); } else RW_LD_DOT(0, hb);
;                 __builtin_amdgcn_sched_barrier(0);
; #pragma unroll
;                 for (int q = 0; q < DB; ++q) {
;                     const int qq = DB * hb + q; const f32x4 k4 = kd[hb & (NB - 1)][q];
;                     aS0 += S2[2 * qq] * (f32x2){k4.x, k4.y}; aS1 += S2[2 * qq + 1] * (f32x2){k4.z, k4.w};
;                     if (MODE == 0) { aC0 += C2[2 * qq] * (f32x2){k4.x, k4.y}; aC1 += C2[2 * qq + 1] * (f32x2){k4.z, k4.w}; }
;                 }
;                 __builtin_amdgcn_sched_barrier(0);
;             }
;             const float nsk = -((aS0.x + aS0.y) + (aS1.x + aS1.y));
;             const float nskC = -((aC0.x + aC0.y) + (aC1.x + aC1.y));
;             f32x2 y0 = {0.f, 0.f}, y1 = {0.f, 0.f};
; #pragma unroll
;             for (int qb = 0; qb < NUB; ++qb) {
;                 if (NB == 2) { if (qb + 1 < NUB) RW_LD_UPD((qb + 1) & 1, qb + 1); } else RW_LD_UPD(0, qb);
;                 __builtin_amdgcn_sched_barrier(0);
; #pragma unroll
;                 for (int q = 0; q < UB; ++q) {
;                     const int qq = UB * qb + q;
;                     const f32x4 w4 = wq[qb & (NB - 1)][q], b4 = bq[qb & (NB - 1)][q], k4 = kq[qb & (NB - 1)][q];
;                     if (MODE == 0) {
;                         S2[2 * qq] = S2[2 * qq] * (f32x2){w4.x, w4.y} + (f32x2){b4.x, b4.y} * nsk;
;                         S2[2 * qq + 1] = S2[2 * qq + 1] * (f32x2){w4.z, w4.w} + (f32x2){b4.z, b4.w} * nsk;
	v_mfma_f32_4x4x1_16b_f32 v[48:51], v234, v194, v[48:51]
	v_mfma_f32_4x4x1_16b_f32 v[56:59], v130, v193, v[56:59]
	v_mfma_f32_4x4x1_16b_f32 v[52:55], v235, v194, v[52:55]
	v_mfma_f32_4x4x1_16b_f32 v[60:63], v131, v193, v[60:63]
	v_mfma_f32_4x4x1_16b_f32 v[56:59], v236, v194, v[56:59]
	s_nop 0
	v_mfma_f32_4x4x1_16b_f32 v[60:63], v237, v194, v[60:63]
	v_pk_fma_f32 v[158:159], v[136:137], v[0:1], 0 op_sel_hi:[1,1,0]
	v_pk_fma_f32 v[160:161], v[138:139], v[2:3], 0 op_sel_hi:[1,1,0]
	ds_read_b128 v[136:139], v196 offset:9408
	v_pk_fma_f32 v[162:163], v[140:141], v[4:5], 0 op_sel_hi:[1,1,0]
	v_pk_fma_f32 v[164:165], v[142:143], v[6:7], 0 op_sel_hi:[1,1,0]
	ds_read_b128 v[140:143], v196 offset:9424
	v_pk_fma_f32 v[158:159], v[144:145], v[8:9], v[158:159]
	v_pk_fma_f32 v[160:161], v[146:147], v[10:11], v[160:161]
	ds_read_b128 v[144:147], v196 offset:9440
	v_pk_fma_f32 v[162:163], v[148:149], v[12:13], v[162:163]
	v_pk_fma_f32 v[164:165], v[150:151], v[14:15], v[164:165]
	ds_read_b128 v[148:151], v196 offset:9456
	v_pk_fma_f32 v[158:159], v[176:177], v[16:17], v[158:159]
	v_pk_fma_f32 v[160:161], v[178:179], v[18:19], v[160:161]
	ds_read_b128 v[176:179], v196 offset:10496
	v_pk_fma_f32 v[162:163], v[180:181], v[20:21], v[162:163]
	v_pk_fma_f32 v[164:165], v[182:183], v[22:23], v[164:165]
	ds_read_b128 v[180:183], v196 offset:10512
	v_pk_fma_f32 v[158:159], v[184:185], v[24:25], v[158:159]
	v_pk_fma_f32 v[160:161], v[186:187], v[26:27], v[160:161]
	ds_read_b128 v[184:187], v196 offset:10528
	v_pk_fma_f32 v[162:163], v[188:189], v[28:29], v[162:163]
	v_pk_fma_f32 v[164:165], v[190:191], v[30:31], v[164:165]
	ds_read_b128 v[188:191], v196 offset:10544
	v_pk_fma_f32 v[158:159], v[200:201], v[32:33], v[158:159]
	v_pk_fma_f32 v[160:161], v[202:203], v[34:35], v[160:161]
	ds_read_b128 v[200:203], v196 offset:10560
	v_pk_fma_f32 v[162:163], v[204:205], v[36:37], v[162:163]
	v_pk_fma_f32 v[164:165], v[206:207], v[38:39], v[164:165]
	ds_read_b128 v[204:207], v196 offset:10576
	v_pk_fma_f32 v[158:159], v[214:215], v[40:41], v[158:159]
	v_pk_fma_f32 v[160:161], v[216:217], v[42:43], v[160:161]
	ds_read_b128 v[214:217], v196 offset:10592
	v_pk_fma_f32 v[162:163], v[238:239], v[44:45], v[162:163]
	v_pk_fma_f32 v[164:165], v[240:241], v[46:47], v[164:165]
	ds_read_b128 v[238:241], v196 offset:10608
	s_waitcnt lgkmcnt(11)
	v_pk_fma_f32 v[158:159], v[136:137], v[48:49], v[158:159]
	v_pk_fma_f32 v[160:161], v[138:139], v[50:51], v[160:161]
	ds_read_b128 v[136:139], v196 offset:10624
	s_waitcnt lgkmcnt(11)
	v_pk_fma_f32 v[162:163], v[140:141], v[52:53], v[162:163]
	v_pk_fma_f32 v[164:165], v[142:143], v[54:55], v[164:165]
	ds_read_b128 v[140:143], v196 offset:10640
	s_waitcnt lgkmcnt(11)
	v_pk_fma_f32 v[158:159], v[144:145], v[56:57], v[158:159]
	v_pk_fma_f32 v[160:161], v[146:147], v[58:59], v[160:161]
	ds_read_b128 v[144:147], v196 offset:10656
	s_waitcnt lgkmcnt(11)
	v_pk_fma_f32 v[162:163], v[148:149], v[60:61], v[162:163]
	v_pk_fma_f32 v[164:165], v[150:151], v[62:63], v[164:165]
	ds_read_b128 v[148:151], v196 offset:10672
	v_pk_add_f32 v[158:159], v[158:159], v[162:163]
	v_pk_add_f32 v[160:161], v[160:161], v[164:165]
	v_add_f32_e32 v198, v158, v159
	v_add_f32_e32 v192, v160, v161
	v_add_f32_e32 v198, v192, v198
	ds_write_b32 v109, v198 offset:8192
	s_waitcnt lgkmcnt(10)
	ds_read_b32 v194, v109 offset:11520
	ds_read_b128 v[124:127], v199 offset:10752
	ds_read_b128 v[230:233], v199 offset:11008
	ds_read_b128 v[128:131], v199 offset:10768
	ds_read_b128 v[234:237], v199 offset:11024
	v_pk_fma_f32 v[158:159], v[0:1], v[176:177], 0 op_sel_hi:[1,1,0]
	v_pk_fma_f32 v[160:161], v[2:3], v[178:179], 0 op_sel_hi:[1,1,0]
	s_waitcnt lgkmcnt(14)
	ds_read_b128 v[176:179], v196 offset:10688
	v_pk_fma_f32 v[162:163], v[4:5], v[180:181], 0 op_sel_hi:[1,1,0]
	v_pk_fma_f32 v[164:165], v[6:7], v[182:183], 0 op_sel_hi:[1,1,0]
	s_waitcnt lgkmcnt(14)
	ds_read_b128 v[180:183], v196 offset:10704
	v_pk_fma_f32 v[158:159], v[8:9], v[184:185], v[158:159]
	v_pk_fma_f32 v[160:161], v[10:11], v[186:187], v[160:161]
	s_waitcnt lgkmcnt(14)
	ds_read_b128 v[184:187], v196 offset:10720
	v_pk_fma_f32 v[162:163], v[12:13], v[188:189], v[162:163]
	v_pk_fma_f32 v[164:165], v[14:15], v[190:191], v[164:165]
	s_waitcnt lgkmcnt(14)
	ds_read_b128 v[188:191], v196 offset:10736
	v_pk_fma_f32 v[158:159], v[16:17], v[200:201], v[158:159]
	v_pk_fma_f32 v[160:161], v[18:19], v[202:203], v[160:161]
	s_waitcnt lgkmcnt(14)
	ds_read_b128 v[200:203], v196 offset:11264
	v_pk_fma_f32 v[162:163], v[20:21], v[204:205], v[162:163]
	v_pk_fma_f32 v[164:165], v[22:23], v[206:207], v[164:165]
	s_waitcnt lgkmcnt(14)
	ds_read_b128 v[204:207], v196 offset:11280
	v_pk_fma_f32 v[158:159], v[24:25], v[214:215], v[158:159]
	v_pk_fma_f32 v[160:161], v[26:27], v[216:217], v[160:161]
	s_waitcnt lgkmcnt(14)
	ds_read_b128 v[214:217], v196 offset:11296
	v_pk_fma_f32 v[162:163], v[28:29], v[238:239], v[162:163]
	v_pk_fma_f32 v[164:165], v[30:31], v[240:241], v[164:165]
	s_waitcnt lgkmcnt(14)
	ds_read_b128 v[238:241], v196 offset:11312
	v_pk_fma_f32 v[158:159], v[32:33], v[136:137], v[158:159]
	v_pk_fma_f32 v[160:161], v[34:35], v[138:139], v[160:161]
	s_waitcnt lgkmcnt(14)
	ds_read_b128 v[136:139], v196 offset:11328
	v_pk_fma_f32 v[162:163], v[36:37], v[140:141], v[162:163]
	v_pk_fma_f32 v[164:165], v[38:39], v[142:143], v[164:165]
	s_waitcnt lgkmcnt(14)
	ds_read_b128 v[140:143], v196 offset:11344
	v_pk_fma_f32 v[158:159], v[40:41], v[144:145], v[158:159]
	v_pk_fma_f32 v[160:161], v[42:43], v[146:147], v[160:161]
	s_waitcnt lgkmcnt(14)
	ds_read_b128 v[144:147], v196 offset:11360
	v_pk_fma_f32 v[162:163], v[44:45], v[148:149], v[162:163]
	v_pk_fma_f32 v[164:165], v[46:47], v[150:151], v[164:165]
	s_waitcnt lgkmcnt(14)
; #define LAS __attribute__((address_space(3)))
; template <int MODE> __device__ __forceinline__ void rwkv_item(const Params& P, int e, int c, int h, LAS float* slab, int lane) {
;     ...
;         for (int s = 0; s < SB; ++s) {
;             const LAS float* st = slab + s * 512;
;             f32x2 aS0 = {0.f, 0.f}, aS1 = {0.f, 0.f}, aC0 = {0.f, 0.f}, aC1 = {0.f, 0.f};
;             constexpr int DB = 4, UB = 2;
;             constexpr int NDB = 16 / DB, NUB = 16 / UB;
;             constexpr int NB = MODE == 1 ? 2 : 1;
;             f32x4 kd[NB][DB];
;             f32x4 wq[NB][UB], bq[NB][UB], kq[NB][UB], rq[NB][MODE == 1 ? UB : 1];
;     ...
;             if (NB == 2) RW_LD_DOT(0, 0);
;             const float v = st[320 + lane];
; #pragma unroll
;             for (int hb = 0; hb < NDB; ++hb) {
;                 if (NB == 2) { if (hb + 1 < NDB) RW_LD_DOT((hb + 1) & 1, hb + 1); else RW_LD_UPD(0, 0); } else RW_LD_DOT(0, hb);
;                 __builtin_amdgcn_sched_barrier(0);
; #pragma unroll
;                 for (int q = 0; q < DB; ++q) {
;                     const int qq = DB * hb + q; const f32x4 k4 = kd[hb & (NB - 1)][q];
;                     aS0 += S2[2 * qq] * (f32x2){k4.x, k4.y}; aS1 += S2[2 * qq + 1] * (f32x2){k4.z, k4.w};
;                     if (MODE == 0) { aC0 += C2[2 * qq] * (f32x2){k4.x, k4.y}; aC1 += C2[2 * qq + 1] * (f32x2){k4.z, k4.w}; }
;                 }
;                 __builtin_amdgcn_sched_barrier(0);
;             }
;             const float nsk = -((aS0.x + aS0.y) + (aS1.x + aS1.y));
;             const float nskC = -((aC0.x + aC0.y) + (aC1.x + aC1.y));
;             f32x2 y0 = {0.f, 0.f}, y1 = {0.f, 0.f};
; #pragma unroll
;             for (int qb = 0; qb < NUB; ++qb) {
;                 if (NB == 2) { if (qb + 1 < NUB) RW_LD_UPD((qb + 1) & 1, qb + 1); } else RW_LD_UPD(0, qb);
;                 __builtin_amdgcn_sched_barrier(0);
; #pragma unroll
;                 for (int q = 0; q < UB; ++q) {
;                     const int qq = UB * qb + q;
;                     const f32x4 w4 = wq[qb & (NB - 1)][q], b4 = bq[qb & (NB - 1)][q], k4 = kq[qb & (NB - 1)][q];
;                     if (MODE == 0) {
;                         S2[2 * qq] = S2[2 * qq] * (f32x2){w4.x, w4.y} + (f32x2){b4.x, b4.y} * nsk;
;                         S2[2 * qq + 1] = S2[2 * qq + 1] * (f32x2){w4.z, w4.w} + (f32x2){b4.z, b4.w} * nsk;
	ds_read_b128 v[148:151], v196 offset:11376
	s_waitcnt lgkmcnt(11)
	v_pk_fma_f32 v[158:159], v[48:49], v[176:177], v[158:159]
	v_pk_fma_f32 v[160:161], v[50:51], v[178:179], v[160:161]
	ds_read_b128 v[176:179], v196 offset:11392
	s_waitcnt lgkmcnt(11)
	v_pk_fma_f32 v[162:163], v[52:53], v[180:181], v[162:163]
	v_pk_fma_f32 v[164:165], v[54:55], v[182:183], v[164:165]
	ds_read_b128 v[180:183], v196 offset:11408
	s_waitcnt lgkmcnt(11)
	v_pk_fma_f32 v[158:159], v[56:57], v[184:185], v[158:159]
	v_pk_fma_f32 v[160:161], v[58:59], v[186:187], v[160:161]
	ds_read_b128 v[184:187], v196 offset:11424
	s_waitcnt lgkmcnt(11)
	v_pk_fma_f32 v[162:163], v[60:61], v[188:189], v[162:163]
	v_pk_fma_f32 v[164:165], v[62:63], v[190:191], v[164:165]
	ds_read_b128 v[188:191], v196 offset:11440
	v_pk_add_f32 v[158:159], v[158:159], v[162:163]
	v_pk_add_f32 v[160:161], v[160:161], v[164:165]
	v_add_f32_e32 v192, v158, v159
	v_add_f32_e32 v198, v160, v161
	v_sub_f32_e64 v193, -v198, v192
	s_nop 1
	v_mfma_f32_4x4x1_16b_f32 v[0:3], v124, v193, v[0:3]
	v_mfma_f32_4x4x1_16b_f32 v[4:7], v125, v193, v[4:7]
	v_mfma_f32_4x4x1_16b_f32 v[0:3], v230, v194, v[0:3]
	v_mfma_f32_4x4x1_16b_f32 v[8:11], v126, v193, v[8:11]
	v_mfma_f32_4x4x1_16b_f32 v[4:7], v231, v194, v[4:7]
	v_mfma_f32_4x4x1_16b_f32 v[12:15], v127, v193, v[12:15]
	v_mfma_f32_4x4x1_16b_f32 v[8:11], v232, v194, v[8:11]
	ds_read_b128 v[124:127], v199 offset:10784
	v_mfma_f32_4x4x1_16b_f32 v[16:19], v128, v193, v[16:19]
	v_mfma_f32_4x4x1_16b_f32 v[12:15], v233, v194, v[12:15]
	ds_read_b128 v[230:233], v199 offset:11040
	v_mfma_f32_4x4x1_16b_f32 v[20:23], v129, v193, v[20:23]
	v_mfma_f32_4x4x1_16b_f32 v[16:19], v234, v194, v[16:19]
	v_mfma_f32_4x4x1_16b_f32 v[24:27], v130, v193, v[24:27]
	v_mfma_f32_4x4x1_16b_f32 v[20:23], v235, v194, v[20:23]
	v_mfma_f32_4x4x1_16b_f32 v[28:31], v131, v193, v[28:31]
	v_mfma_f32_4x4x1_16b_f32 v[24:27], v236, v194, v[24:27]
	ds_read_b128 v[128:131], v199 offset:10800
	s_waitcnt lgkmcnt(2)
	v_mfma_f32_4x4x1_16b_f32 v[32:35], v124, v193, v[32:35]
	v_mfma_f32_4x4x1_16b_f32 v[28:31], v237, v194, v[28:31]
	ds_read_b128 v[234:237], v199 offset:11056
	v_mfma_f32_4x4x1_16b_f32 v[36:39], v125, v193, v[36:39]
	s_waitcnt lgkmcnt(2)
	v_mfma_f32_4x4x1_16b_f32 v[32:35], v230, v194, v[32:35]
	v_mfma_f32_4x4x1_16b_f32 v[40:43], v126, v193, v[40:43]
	v_mfma_f32_4x4x1_16b_f32 v[36:39], v231, v194, v[36:39]
	v_mfma_f32_4x4x1_16b_f32 v[44:47], v127, v193, v[44:47]
	v_mfma_f32_4x4x1_16b_f32 v[40:43], v232, v194, v[40:43]
	s_waitcnt lgkmcnt(1)
	v_mfma_f32_4x4x1_16b_f32 v[48:51], v128, v193, v[48:51]
	v_mfma_f32_4x4x1_16b_f32 v[44:47], v233, v194, v[44:47]
	v_mfma_f32_4x4x1_16b_f32 v[52:55], v129, v193, v[52:55]
	s_waitcnt lgkmcnt(0)
	v_mfma_f32_4x4x1_16b_f32 v[48:51], v234, v194, v[48:51]
	v_mfma_f32_4x4x1_16b_f32 v[56:59], v130, v193, v[56:59]
	v_mfma_f32_4x4x1_16b_f32 v[52:55], v235, v194, v[52:55]
	v_mfma_f32_4x4x1_16b_f32 v[60:63], v131, v193, v[60:63]
	v_mfma_f32_4x4x1_16b_f32 v[56:59], v236, v194, v[56:59]
	s_nop 0
	v_mfma_f32_4x4x1_16b_f32 v[60:63], v237, v194, v[60:63]
	v_pk_fma_f32 v[158:159], v[200:201], v[0:1], 0 op_sel_hi:[1,1,0]
	v_pk_fma_f32 v[160:161], v[202:203], v[2:3], 0 op_sel_hi:[1,1,0]
	ds_read_b128 v[200:203], v196 offset:11456
	v_pk_fma_f32 v[162:163], v[204:205], v[4:5], 0 op_sel_hi:[1,1,0]
	v_pk_fma_f32 v[164:165], v[206:207], v[6:7], 0 op_sel_hi:[1,1,0]
	ds_read_b128 v[204:207], v196 offset:11472
	v_pk_fma_f32 v[158:159], v[214:215], v[8:9], v[158:159]
	v_pk_fma_f32 v[160:161], v[216:217], v[10:11], v[160:161]
	ds_read_b128 v[214:217], v196 offset:11488
	v_pk_fma_f32 v[162:163], v[238:239], v[12:13], v[162:163]
	v_pk_fma_f32 v[164:165], v[240:241], v[14:15], v[164:165]
	ds_read_b128 v[238:241], v196 offset:11504
	v_pk_fma_f32 v[158:159], v[136:137], v[16:17], v[158:159]
	v_pk_fma_f32 v[160:161], v[138:139], v[18:19], v[160:161]
	ds_read_b128 v[136:139], v196 offset:12544
	v_pk_fma_f32 v[162:163], v[140:141], v[20:21], v[162:163]
	v_pk_fma_f32 v[164:165], v[142:143], v[22:23], v[164:165]
	ds_read_b128 v[140:143], v196 offset:12560
	v_pk_fma_f32 v[158:159], v[144:145], v[24:25], v[158:159]
	v_pk_fma_f32 v[160:161], v[146:147], v[26:27], v[160:161]
	ds_read_b128 v[144:147], v196 offset:12576
	v_pk_fma_f32 v[162:163], v[148:149], v[28:29], v[162:163]
	v_pk_fma_f32 v[164:165], v[150:151], v[30:31], v[164:165]
	ds_read_b128 v[148:151], v196 offset:12592
	v_pk_fma_f32 v[158:159], v[176:177], v[32:33], v[158:159]
	v_pk_fma_f32 v[160:161], v[178:179], v[34:35], v[160:161]
	ds_read_b128 v[176:179], v196 offset:12608
	v_pk_fma_f32 v[162:163], v[180:181], v[36:37], v[162:163]
	v_pk_fma_f32 v[164:165], v[182:183], v[38:39], v[164:165]
	ds_read_b128 v[180:183], v196 offset:12624
	v_pk_fma_f32 v[158:159], v[184:185], v[40:41], v[158:159]
	v_pk_fma_f32 v[160:161], v[186:187], v[42:43], v[160:161]
	ds_read_b128 v[184:187], v196 offset:12640
	v_pk_fma_f32 v[162:163], v[188:189], v[44:45], v[162:163]
	v_pk_fma_f32 v[164:165], v[190:191], v[46:47], v[164:165]
	ds_read_b128 v[188:191], v196 offset:12656
	s_waitcnt lgkmcnt(11)
	v_pk_fma_f32 v[158:159], v[200:201], v[48:49], v[158:159]
	v_pk_fma_f32 v[160:161], v[202:203], v[50:51], v[160:161]
	ds_read_b128 v[200:203], v196 offset:12672
	s_waitcnt lgkmcnt(11)
	v_pk_fma_f32 v[162:163], v[204:205], v[52:53], v[162:163]
	v_pk_fma_f32 v[164:165], v[206:207], v[54:55], v[164:165]
	ds_read_b128 v[204:207], v196 offset:12688
	s_waitcnt lgkmcnt(11)
	v_pk_fma_f32 v[158:159], v[214:215], v[56:57], v[158:159]
	v_pk_fma_f32 v[160:161], v[216:217], v[58:59], v[160:161]
	ds_read_b128 v[214:217], v196 offset:12704
	s_waitcnt lgkmcnt(11)
; #define LAS __attribute__((address_space(3)))
; template <int MODE> __device__ __forceinline__ void rwkv_item(const Params& P, int e, int c, int h, LAS float* slab, int lane) {
;     ...
;         for (int s = 0; s < SB; ++s) {
;             const LAS float* st = slab + s * 512;
;             f32x2 aS0 = {0.f, 0.f}, aS1 = {0.f, 0.f}, aC0 = {0.f, 0.f}, aC1 = {0.f, 0.f};
;             constexpr int DB = 4, UB = 2;
;             constexpr int NDB = 16 / DB, NUB = 16 / UB;
;             constexpr int NB = MODE == 1 ? 2 : 1;
;             f32x4 kd[NB][DB];
;             f32x4 wq[NB][UB], bq[NB][UB], kq[NB][UB], rq[NB][MODE == 1 ? UB : 1];
;     ...
;             if (NB == 2) RW_LD_DOT(0, 0);
;             const float v = st[320 + lane];
; #pragma unroll
;             for (int hb = 0; hb < NDB; ++hb) {
;                 if (NB == 2) { if (hb + 1 < NDB) RW_LD_DOT((hb + 1) & 1, hb + 1); else RW_LD_UPD(0, 0); } else RW_LD_DOT(0, hb);
;                 __builtin_amdgcn_sched_barrier(0);
; #pragma unroll
;                 for (int q = 0; q < DB; ++q) {
;                     const int qq = DB * hb + q; const f32x4 k4 = kd[hb & (NB - 1)][q];
;                     aS0 += S2[2 * qq] * (f32x2){k4.x, k4.y}; aS1 += S2[2 * qq + 1] * (f32x2){k4.z, k4.w};
;                     if (MODE == 0) { aC0 += C2[2 * qq] * (f32x2){k4.x, k4.y}; aC1 += C2[2 * qq + 1] * (f32x2){k4.z, k4.w}; }
;                 }
;                 __builtin_amdgcn_sched_barrier(0);
;             }
;             const float nsk = -((aS0.x + aS0.y) + (aS1.x + aS1.y));
;             const float nskC = -((aC0.x + aC0.y) + (aC1.x + aC1.y));
;             f32x2 y0 = {0.f, 0.f}, y1 = {0.f, 0.f};
; #pragma unroll
;             for (int qb = 0; qb < NUB; ++qb) {
;                 if (NB == 2) { if (qb + 1 < NUB) RW_LD_UPD((qb + 1) & 1, qb + 1); } else RW_LD_UPD(0, qb);
;                 __builtin_amdgcn_sched_barrier(0);
; #pragma unroll
;                 for (int q = 0; q < UB; ++q) {
;                     const int qq = UB * qb + q;
;                     const f32x4 w4 = wq[qb & (NB - 1)][q], b4 = bq[qb & (NB - 1)][q], k4 = kq[qb & (NB - 1)][q];
;                     if (MODE == 0) {
;                         S2[2 * qq] = S2[2 * qq] * (f32x2){w4.x, w4.y} + (f32x2){b4.x, b4.y} * nsk;
;                         S2[2 * qq + 1] = S2[2 * qq + 1] * (f32x2){w4.z, w4.w} + (f32x2){b4.z, b4.w} * nsk;
	v_pk_fma_f32 v[162:163], v[238:239], v[60:61], v[162:163]
	v_pk_fma_f32 v[164:165], v[240:241], v[62:63], v[164:165]
	ds_read_b128 v[238:241], v196 offset:12720
	v_pk_add_f32 v[158:159], v[158:159], v[162:163]
	v_pk_add_f32 v[160:161], v[160:161], v[164:165]
	v_add_f32_e32 v198, v158, v159
	v_add_f32_e32 v192, v160, v161
	v_add_f32_e32 v198, v192, v198
	ds_write_b32 v109, v198 offset:10240
	s_waitcnt lgkmcnt(10)
	ds_read_b32 v194, v109 offset:13568
	ds_read_b128 v[124:127], v199 offset:12800
	ds_read_b128 v[230:233], v199 offset:13056
	ds_read_b128 v[128:131], v199 offset:12816
	ds_read_b128 v[234:237], v199 offset:13072
	v_pk_fma_f32 v[158:159], v[0:1], v[136:137], 0 op_sel_hi:[1,1,0]
	v_pk_fma_f32 v[160:161], v[2:3], v[138:139], 0 op_sel_hi:[1,1,0]
	s_waitcnt lgkmcnt(14)
	ds_read_b128 v[136:139], v196 offset:12736
	v_pk_fma_f32 v[162:163], v[4:5], v[140:141], 0 op_sel_hi:[1,1,0]
	v_pk_fma_f32 v[164:165], v[6:7], v[142:143], 0 op_sel_hi:[1,1,0]
	s_waitcnt lgkmcnt(14)
	ds_read_b128 v[140:143], v196 offset:12752
	v_pk_fma_f32 v[158:159], v[8:9], v[144:145], v[158:159]
	v_pk_fma_f32 v[160:161], v[10:11], v[146:147], v[160:161]
	s_waitcnt lgkmcnt(14)
	ds_read_b128 v[144:147], v196 offset:12768
	v_pk_fma_f32 v[162:163], v[12:13], v[148:149], v[162:163]
	v_pk_fma_f32 v[164:165], v[14:15], v[150:151], v[164:165]
	s_waitcnt lgkmcnt(14)
	ds_read_b128 v[148:151], v196 offset:12784
	v_pk_fma_f32 v[158:159], v[16:17], v[176:177], v[158:159]
	v_pk_fma_f32 v[160:161], v[18:19], v[178:179], v[160:161]
	s_waitcnt lgkmcnt(14)
	ds_read_b128 v[176:179], v196 offset:13312
	v_pk_fma_f32 v[162:163], v[20:21], v[180:181], v[162:163]
	v_pk_fma_f32 v[164:165], v[22:23], v[182:183], v[164:165]
	s_waitcnt lgkmcnt(14)
	ds_read_b128 v[180:183], v196 offset:13328
	v_pk_fma_f32 v[158:159], v[24:25], v[184:185], v[158:159]
	v_pk_fma_f32 v[160:161], v[26:27], v[186:187], v[160:161]
	s_waitcnt lgkmcnt(14)
	ds_read_b128 v[184:187], v196 offset:13344
	v_pk_fma_f32 v[162:163], v[28:29], v[188:189], v[162:163]
	v_pk_fma_f32 v[164:165], v[30:31], v[190:191], v[164:165]
	s_waitcnt lgkmcnt(14)
	ds_read_b128 v[188:191], v196 offset:13360
	v_pk_fma_f32 v[158:159], v[32:33], v[200:201], v[158:159]
	v_pk_fma_f32 v[160:161], v[34:35], v[202:203], v[160:161]
	s_waitcnt lgkmcnt(14)
	ds_read_b128 v[200:203], v196 offset:13376
	v_pk_fma_f32 v[162:163], v[36:37], v[204:205], v[162:163]
	v_pk_fma_f32 v[164:165], v[38:39], v[206:207], v[164:165]
	s_waitcnt lgkmcnt(14)
	ds_read_b128 v[204:207], v196 offset:13392
	v_pk_fma_f32 v[158:159], v[40:41], v[214:215], v[158:159]
	v_pk_fma_f32 v[160:161], v[42:43], v[216:217], v[160:161]
	s_waitcnt lgkmcnt(14)
	ds_read_b128 v[214:217], v196 offset:13408
	v_pk_fma_f32 v[162:163], v[44:45], v[238:239], v[162:163]
	v_pk_fma_f32 v[164:165], v[46:47], v[240:241], v[164:165]
	s_waitcnt lgkmcnt(14)
	ds_read_b128 v[238:241], v196 offset:13424
	s_waitcnt lgkmcnt(11)
	v_pk_fma_f32 v[158:159], v[48:49], v[136:137], v[158:159]
	v_pk_fma_f32 v[160:161], v[50:51], v[138:139], v[160:161]
	ds_read_b128 v[136:139], v196 offset:13440
	s_waitcnt lgkmcnt(11)
	v_pk_fma_f32 v[162:163], v[52:53], v[140:141], v[162:163]
	v_pk_fma_f32 v[164:165], v[54:55], v[142:143], v[164:165]
	ds_read_b128 v[140:143], v196 offset:13456
	s_waitcnt lgkmcnt(11)
	v_pk_fma_f32 v[158:159], v[56:57], v[144:145], v[158:159]
	v_pk_fma_f32 v[160:161], v[58:59], v[146:147], v[160:161]
	ds_read_b128 v[144:147], v196 offset:13472
	s_waitcnt lgkmcnt(11)
	v_pk_fma_f32 v[162:163], v[60:61], v[148:149], v[162:163]
	v_pk_fma_f32 v[164:165], v[62:63], v[150:151], v[164:165]
	ds_read_b128 v[148:151], v196 offset:13488
	v_pk_add_f32 v[158:159], v[158:159], v[162:163]
	v_pk_add_f32 v[160:161], v[160:161], v[164:165]
	v_add_f32_e32 v192, v158, v159
	v_add_f32_e32 v198, v160, v161
	v_sub_f32_e64 v193, -v198, v192
	s_nop 1
	v_mfma_f32_4x4x1_16b_f32 v[0:3], v124, v193, v[0:3]
	v_mfma_f32_4x4x1_16b_f32 v[4:7], v125, v193, v[4:7]
	v_mfma_f32_4x4x1_16b_f32 v[0:3], v230, v194, v[0:3]
	v_mfma_f32_4x4x1_16b_f32 v[8:11], v126, v193, v[8:11]
	v_mfma_f32_4x4x1_16b_f32 v[4:7], v231, v194, v[4:7]
	v_mfma_f32_4x4x1_16b_f32 v[12:15], v127, v193, v[12:15]
	v_mfma_f32_4x4x1_16b_f32 v[8:11], v232, v194, v[8:11]
	ds_read_b128 v[124:127], v199 offset:12832
	v_mfma_f32_4x4x1_16b_f32 v[16:19], v128, v193, v[16:19]
	v_mfma_f32_4x4x1_16b_f32 v[12:15], v233, v194, v[12:15]
	ds_read_b128 v[230:233], v199 offset:13088
	v_mfma_f32_4x4x1_16b_f32 v[20:23], v129, v193, v[20:23]
	v_mfma_f32_4x4x1_16b_f32 v[16:19], v234, v194, v[16:19]
	v_mfma_f32_4x4x1_16b_f32 v[24:27], v130, v193, v[24:27]
	v_mfma_f32_4x4x1_16b_f32 v[20:23], v235, v194, v[20:23]
	v_mfma_f32_4x4x1_16b_f32 v[28:31], v131, v193, v[28:31]
	v_mfma_f32_4x4x1_16b_f32 v[24:27], v236, v194, v[24:27]
	ds_read_b128 v[128:131], v199 offset:12848
	s_waitcnt lgkmcnt(2)
	v_mfma_f32_4x4x1_16b_f32 v[32:35], v124, v193, v[32:35]
	v_mfma_f32_4x4x1_16b_f32 v[28:31], v237, v194, v[28:31]
	ds_read_b128 v[234:237], v199 offset:13104
	v_mfma_f32_4x4x1_16b_f32 v[36:39], v125, v193, v[36:39]
	s_waitcnt lgkmcnt(2)
	v_mfma_f32_4x4x1_16b_f32 v[32:35], v230, v194, v[32:35]
	v_mfma_f32_4x4x1_16b_f32 v[40:43], v126, v193, v[40:43]
	v_mfma_f32_4x4x1_16b_f32 v[36:39], v231, v194, v[36:39]
	v_mfma_f32_4x4x1_16b_f32 v[44:47], v127, v193, v[44:47]
	v_mfma_f32_4x4x1_16b_f32 v[40:43], v232, v194, v[40:43]
	s_waitcnt lgkmcnt(1)
	v_mfma_f32_4x4x1_16b_f32 v[48:51], v128, v193, v[48:51]
	v_mfma_f32_4x4x1_16b_f32 v[44:47], v233, v194, v[44:47]
	v_mfma_f32_4x4x1_16b_f32 v[52:55], v129, v193, v[52:55]
	s_waitcnt lgkmcnt(0)
; #define LAS __attribute__((address_space(3)))
; template <int MODE> __device__ __forceinline__ void rwkv_item(const Params& P, int e, int c, int h, LAS float* slab, int lane) {
;     ...
;         for (int s = 0; s < SB; ++s) {
;             const LAS float* st = slab + s * 512;
;             f32x2 aS0 = {0.f, 0.f}, aS1 = {0.f, 0.f}, aC0 = {0.f, 0.f}, aC1 = {0.f, 0.f};
;             constexpr int DB = 4, UB = 2;
;             constexpr int NDB = 16 / DB, NUB = 16 / UB;
;             constexpr int NB = MODE == 1 ? 2 : 1;
;             f32x4 kd[NB][DB];
;             f32x4 wq[NB][UB], bq[NB][UB], kq[NB][UB], rq[NB][MODE == 1 ? UB : 1];
;     ...
;             if (NB == 2) RW_LD_DOT(0, 0);
;             const float v = st[320 + lane];
; #pragma unroll
;             for (int hb = 0; hb < NDB; ++hb) {
;                 if (NB == 2) { if (hb + 1 < NDB) RW_LD_DOT((hb + 1) & 1, hb + 1); else RW_LD_UPD(0, 0); } else RW_LD_DOT(0, hb);
;                 __builtin_amdgcn_sched_barrier(0);
; #pragma unroll
;                 for (int q = 0; q < DB; ++q) {
;                     const int qq = DB * hb + q; const f32x4 k4 = kd[hb & (NB - 1)][q];
;                     aS0 += S2[2 * qq] * (f32x2){k4.x, k4.y}; aS1 += S2[2 * qq + 1] * (f32x2){k4.z, k4.w};
;                     if (MODE == 0) { aC0 += C2[2 * qq] * (f32x2){k4.x, k4.y}; aC1 += C2[2 * qq + 1] * (f32x2){k4.z, k4.w}; }
;                 }
;                 __builtin_amdgcn_sched_barrier(0);
;             }
;             const float nsk = -((aS0.x + aS0.y) + (aS1.x + aS1.y));
;             const float nskC = -((aC0.x + aC0.y) + (aC1.x + aC1.y));
;             f32x2 y0 = {0.f, 0.f}, y1 = {0.f, 0.f};
; #pragma unroll
;             for (int qb = 0; qb < NUB; ++qb) {
;                 if (NB == 2) { if (qb + 1 < NUB) RW_LD_UPD((qb + 1) & 1, qb + 1); } else RW_LD_UPD(0, qb);
;                 __builtin_amdgcn_sched_barrier(0);
; #pragma unroll
;                 for (int q = 0; q < UB; ++q) {
;                     const int qq = UB * qb + q;
;                     const f32x4 w4 = wq[qb & (NB - 1)][q], b4 = bq[qb & (NB - 1)][q], k4 = kq[qb & (NB - 1)][q];
;                     if (MODE == 0) {
;                         S2[2 * qq] = S2[2 * qq] * (f32x2){w4.x, w4.y} + (f32x2){b4.x, b4.y} * nsk;
;                         S2[2 * qq + 1] = S2[2 * qq + 1] * (f32x2){w4.z, w4.w} + (f32x2){b4.z, b4.w} * nsk;
	v_mfma_f32_4x4x1_16b_f32 v[48:51], v234, v194, v[48:51]
	v_mfma_f32_4x4x1_16b_f32 v[56:59], v130, v193, v[56:59]
	v_mfma_f32_4x4x1_16b_f32 v[52:55], v235, v194, v[52:55]
	v_mfma_f32_4x4x1_16b_f32 v[60:63], v131, v193, v[60:63]
	v_mfma_f32_4x4x1_16b_f32 v[56:59], v236, v194, v[56:59]
	s_nop 0
	v_mfma_f32_4x4x1_16b_f32 v[60:63], v237, v194, v[60:63]
	v_pk_fma_f32 v[158:159], v[176:177], v[0:1], 0 op_sel_hi:[1,1,0]
	v_pk_fma_f32 v[160:161], v[178:179], v[2:3], 0 op_sel_hi:[1,1,0]
	ds_read_b128 v[176:179], v196 offset:13504
	v_pk_fma_f32 v[162:163], v[180:181], v[4:5], 0 op_sel_hi:[1,1,0]
	v_pk_fma_f32 v[164:165], v[182:183], v[6:7], 0 op_sel_hi:[1,1,0]
	ds_read_b128 v[180:183], v196 offset:13520
	v_pk_fma_f32 v[158:159], v[184:185], v[8:9], v[158:159]
	v_pk_fma_f32 v[160:161], v[186:187], v[10:11], v[160:161]
	ds_read_b128 v[184:187], v196 offset:13536
	v_pk_fma_f32 v[162:163], v[188:189], v[12:13], v[162:163]
	v_pk_fma_f32 v[164:165], v[190:191], v[14:15], v[164:165]
	ds_read_b128 v[188:191], v196 offset:13552
	v_pk_fma_f32 v[158:159], v[200:201], v[16:17], v[158:159]
	v_pk_fma_f32 v[160:161], v[202:203], v[18:19], v[160:161]
	ds_read_b128 v[200:203], v196 offset:14592
	v_pk_fma_f32 v[162:163], v[204:205], v[20:21], v[162:163]
	v_pk_fma_f32 v[164:165], v[206:207], v[22:23], v[164:165]
	ds_read_b128 v[204:207], v196 offset:14608
	v_pk_fma_f32 v[158:159], v[214:215], v[24:25], v[158:159]
	v_pk_fma_f32 v[160:161], v[216:217], v[26:27], v[160:161]
	ds_read_b128 v[214:217], v196 offset:14624
	v_pk_fma_f32 v[162:163], v[238:239], v[28:29], v[162:163]
	v_pk_fma_f32 v[164:165], v[240:241], v[30:31], v[164:165]
	ds_read_b128 v[238:241], v196 offset:14640
	v_pk_fma_f32 v[158:159], v[136:137], v[32:33], v[158:159]
	v_pk_fma_f32 v[160:161], v[138:139], v[34:35], v[160:161]
	ds_read_b128 v[136:139], v196 offset:14656
	v_pk_fma_f32 v[162:163], v[140:141], v[36:37], v[162:163]
	v_pk_fma_f32 v[164:165], v[142:143], v[38:39], v[164:165]
	ds_read_b128 v[140:143], v196 offset:14672
	v_pk_fma_f32 v[158:159], v[144:145], v[40:41], v[158:159]
	v_pk_fma_f32 v[160:161], v[146:147], v[42:43], v[160:161]
	ds_read_b128 v[144:147], v196 offset:14688
	v_pk_fma_f32 v[162:163], v[148:149], v[44:45], v[162:163]
	v_pk_fma_f32 v[164:165], v[150:151], v[46:47], v[164:165]
	ds_read_b128 v[148:151], v196 offset:14704
	s_waitcnt lgkmcnt(11)
	v_pk_fma_f32 v[158:159], v[176:177], v[48:49], v[158:159]
	v_pk_fma_f32 v[160:161], v[178:179], v[50:51], v[160:161]
	ds_read_b128 v[176:179], v196 offset:14720
	s_waitcnt lgkmcnt(11)
	v_pk_fma_f32 v[162:163], v[180:181], v[52:53], v[162:163]
	v_pk_fma_f32 v[164:165], v[182:183], v[54:55], v[164:165]
	ds_read_b128 v[180:183], v196 offset:14736
	s_waitcnt lgkmcnt(11)
	v_pk_fma_f32 v[158:159], v[184:185], v[56:57], v[158:159]
	v_pk_fma_f32 v[160:161], v[186:187], v[58:59], v[160:161]
	ds_read_b128 v[184:187], v196 offset:14752
	s_waitcnt lgkmcnt(11)
	v_pk_fma_f32 v[162:163], v[188:189], v[60:61], v[162:163]
	v_pk_fma_f32 v[164:165], v[190:191], v[62:63], v[164:165]
	ds_read_b128 v[188:191], v196 offset:14768
	v_pk_add_f32 v[158:159], v[158:159], v[162:163]
	v_pk_add_f32 v[160:161], v[160:161], v[164:165]
	v_add_f32_e32 v198, v158, v159
	v_add_f32_e32 v192, v160, v161
	v_add_f32_e32 v198, v192, v198
	ds_write_b32 v109, v198 offset:12288
	s_waitcnt lgkmcnt(10)
	ds_read_b32 v194, v109 offset:15616
	ds_read_b128 v[124:127], v199 offset:14848
	ds_read_b128 v[230:233], v199 offset:15104
	ds_read_b128 v[128:131], v199 offset:14864
	ds_read_b128 v[234:237], v199 offset:15120
	v_pk_fma_f32 v[158:159], v[0:1], v[200:201], 0 op_sel_hi:[1,1,0]
	v_pk_fma_f32 v[160:161], v[2:3], v[202:203], 0 op_sel_hi:[1,1,0]
	s_waitcnt lgkmcnt(14)
	ds_read_b128 v[200:203], v196 offset:14784
	v_pk_fma_f32 v[162:163], v[4:5], v[204:205], 0 op_sel_hi:[1,1,0]
	v_pk_fma_f32 v[164:165], v[6:7], v[206:207], 0 op_sel_hi:[1,1,0]
	s_waitcnt lgkmcnt(14)
	ds_read_b128 v[204:207], v196 offset:14800
	v_pk_fma_f32 v[158:159], v[8:9], v[214:215], v[158:159]
	v_pk_fma_f32 v[160:161], v[10:11], v[216:217], v[160:161]
	s_waitcnt lgkmcnt(14)
	ds_read_b128 v[214:217], v196 offset:14816
	v_pk_fma_f32 v[162:163], v[12:13], v[238:239], v[162:163]
	v_pk_fma_f32 v[164:165], v[14:15], v[240:241], v[164:165]
	s_waitcnt lgkmcnt(14)
	ds_read_b128 v[238:241], v196 offset:14832
	v_pk_fma_f32 v[158:159], v[16:17], v[136:137], v[158:159]
	v_pk_fma_f32 v[160:161], v[18:19], v[138:139], v[160:161]
	s_waitcnt lgkmcnt(14)
	ds_read_b128 v[136:139], v196 offset:15360
	v_pk_fma_f32 v[162:163], v[20:21], v[140:141], v[162:163]
	v_pk_fma_f32 v[164:165], v[22:23], v[142:143], v[164:165]
	s_waitcnt lgkmcnt(14)
	ds_read_b128 v[140:143], v196 offset:15376
	v_pk_fma_f32 v[158:159], v[24:25], v[144:145], v[158:159]
	v_pk_fma_f32 v[160:161], v[26:27], v[146:147], v[160:161]
	s_waitcnt lgkmcnt(14)
	ds_read_b128 v[144:147], v196 offset:15392
	v_pk_fma_f32 v[162:163], v[28:29], v[148:149], v[162:163]
	v_pk_fma_f32 v[164:165], v[30:31], v[150:151], v[164:165]
	s_waitcnt lgkmcnt(14)
	ds_read_b128 v[148:151], v196 offset:15408
	v_pk_fma_f32 v[158:159], v[32:33], v[176:177], v[158:159]
	v_pk_fma_f32 v[160:161], v[34:35], v[178:179], v[160:161]
	s_waitcnt lgkmcnt(14)
	ds_read_b128 v[176:179], v196 offset:15424
	v_pk_fma_f32 v[162:163], v[36:37], v[180:181], v[162:163]
	v_pk_fma_f32 v[164:165], v[38:39], v[182:183], v[164:165]
	s_waitcnt lgkmcnt(14)
	ds_read_b128 v[180:183], v196 offset:15440
	v_pk_fma_f32 v[158:159], v[40:41], v[184:185], v[158:159]
	v_pk_fma_f32 v[160:161], v[42:43], v[186:187], v[160:161]
	s_waitcnt lgkmcnt(14)
	ds_read_b128 v[184:187], v196 offset:15456
	v_pk_fma_f32 v[162:163], v[44:45], v[188:189], v[162:163]
	v_pk_fma_f32 v[164:165], v[46:47], v[190:191], v[164:165]
	s_waitcnt lgkmcnt(14)
; #define LAS __attribute__((address_space(3)))
; template <int MODE> __device__ __forceinline__ void rwkv_item(const Params& P, int e, int c, int h, LAS float* slab, int lane) {
;     ...
;         for (int s = 0; s < SB; ++s) {
;             const LAS float* st = slab + s * 512;
;             f32x2 aS0 = {0.f, 0.f}, aS1 = {0.f, 0.f}, aC0 = {0.f, 0.f}, aC1 = {0.f, 0.f};
;             constexpr int DB = 4, UB = 2;
;             constexpr int NDB = 16 / DB, NUB = 16 / UB;
;             constexpr int NB = MODE == 1 ? 2 : 1;
;             f32x4 kd[NB][DB];
;             f32x4 wq[NB][UB], bq[NB][UB], kq[NB][UB], rq[NB][MODE == 1 ? UB : 1];
;     ...
;             if (NB == 2) RW_LD_DOT(0, 0);
;             const float v = st[320 + lane];
; #pragma unroll
;             for (int hb = 0; hb < NDB; ++hb) {
;                 if (NB == 2) { if (hb + 1 < NDB) RW_LD_DOT((hb + 1) & 1, hb + 1); else RW_LD_UPD(0, 0); } else RW_LD_DOT(0, hb);
;                 __builtin_amdgcn_sched_barrier(0);
; #pragma unroll
;                 for (int q = 0; q < DB; ++q) {
;                     const int qq = DB * hb + q; const f32x4 k4 = kd[hb & (NB - 1)][q];
;                     aS0 += S2[2 * qq] * (f32x2){k4.x, k4.y}; aS1 += S2[2 * qq + 1] * (f32x2){k4.z, k4.w};
;                     if (MODE == 0) { aC0 += C2[2 * qq] * (f32x2){k4.x, k4.y}; aC1 += C2[2 * qq + 1] * (f32x2){k4.z, k4.w}; }
;                 }
;                 __builtin_amdgcn_sched_barrier(0);
;             }
;             const float nsk = -((aS0.x + aS0.y) + (aS1.x + aS1.y));
;             const float nskC = -((aC0.x + aC0.y) + (aC1.x + aC1.y));
;             f32x2 y0 = {0.f, 0.f}, y1 = {0.f, 0.f};
; #pragma unroll
;             for (int qb = 0; qb < NUB; ++qb) {
;                 if (NB == 2) { if (qb + 1 < NUB) RW_LD_UPD((qb + 1) & 1, qb + 1); } else RW_LD_UPD(0, qb);
;                 __builtin_amdgcn_sched_barrier(0);
; #pragma unroll
;                 for (int q = 0; q < UB; ++q) {
;                     const int qq = UB * qb + q;
;                     const f32x4 w4 = wq[qb & (NB - 1)][q], b4 = bq[qb & (NB - 1)][q], k4 = kq[qb & (NB - 1)][q];
;                     if (MODE == 0) {
;                         S2[2 * qq] = S2[2 * qq] * (f32x2){w4.x, w4.y} + (f32x2){b4.x, b4.y} * nsk;
;                         S2[2 * qq + 1] = S2[2 * qq + 1] * (f32x2){w4.z, w4.w} + (f32x2){b4.z, b4.w} * nsk;
	ds_read_b128 v[188:191], v196 offset:15472
	s_waitcnt lgkmcnt(11)
	v_pk_fma_f32 v[158:159], v[48:49], v[200:201], v[158:159]
	v_pk_fma_f32 v[160:161], v[50:51], v[202:203], v[160:161]
	ds_read_b128 v[200:203], v196 offset:15488
	s_waitcnt lgkmcnt(11)
	v_pk_fma_f32 v[162:163], v[52:53], v[204:205], v[162:163]
	v_pk_fma_f32 v[164:165], v[54:55], v[206:207], v[164:165]
	ds_read_b128 v[204:207], v196 offset:15504
	s_waitcnt lgkmcnt(11)
	v_pk_fma_f32 v[158:159], v[56:57], v[214:215], v[158:159]
	v_pk_fma_f32 v[160:161], v[58:59], v[216:217], v[160:161]
	ds_read_b128 v[214:217], v196 offset:15520
	s_waitcnt lgkmcnt(11)
	v_pk_fma_f32 v[162:163], v[60:61], v[238:239], v[162:163]
	v_pk_fma_f32 v[164:165], v[62:63], v[240:241], v[164:165]
	ds_read_b128 v[238:241], v196 offset:15536
	v_pk_add_f32 v[158:159], v[158:159], v[162:163]
	v_pk_add_f32 v[160:161], v[160:161], v[164:165]
	v_add_f32_e32 v192, v158, v159
	v_add_f32_e32 v198, v160, v161
	v_sub_f32_e64 v193, -v198, v192
	s_nop 1
	v_mfma_f32_4x4x1_16b_f32 v[0:3], v124, v193, v[0:3]
	v_mfma_f32_4x4x1_16b_f32 v[4:7], v125, v193, v[4:7]
	v_mfma_f32_4x4x1_16b_f32 v[0:3], v230, v194, v[0:3]
	v_mfma_f32_4x4x1_16b_f32 v[8:11], v126, v193, v[8:11]
	v_mfma_f32_4x4x1_16b_f32 v[4:7], v231, v194, v[4:7]
	v_mfma_f32_4x4x1_16b_f32 v[12:15], v127, v193, v[12:15]
	v_mfma_f32_4x4x1_16b_f32 v[8:11], v232, v194, v[8:11]
	ds_read_b128 v[124:127], v199 offset:14880
	v_mfma_f32_4x4x1_16b_f32 v[16:19], v128, v193, v[16:19]
	v_mfma_f32_4x4x1_16b_f32 v[12:15], v233, v194, v[12:15]
	ds_read_b128 v[230:233], v199 offset:15136
	v_mfma_f32_4x4x1_16b_f32 v[20:23], v129, v193, v[20:23]
	v_mfma_f32_4x4x1_16b_f32 v[16:19], v234, v194, v[16:19]
	v_mfma_f32_4x4x1_16b_f32 v[24:27], v130, v193, v[24:27]
	v_mfma_f32_4x4x1_16b_f32 v[20:23], v235, v194, v[20:23]
	v_mfma_f32_4x4x1_16b_f32 v[28:31], v131, v193, v[28:31]
	v_mfma_f32_4x4x1_16b_f32 v[24:27], v236, v194, v[24:27]
	ds_read_b128 v[128:131], v199 offset:14896
	s_waitcnt lgkmcnt(2)
	v_mfma_f32_4x4x1_16b_f32 v[32:35], v124, v193, v[32:35]
	v_mfma_f32_4x4x1_16b_f32 v[28:31], v237, v194, v[28:31]
	ds_read_b128 v[234:237], v199 offset:15152
	v_mfma_f32_4x4x1_16b_f32 v[36:39], v125, v193, v[36:39]
	s_waitcnt lgkmcnt(2)
	v_mfma_f32_4x4x1_16b_f32 v[32:35], v230, v194, v[32:35]
	v_mfma_f32_4x4x1_16b_f32 v[40:43], v126, v193, v[40:43]
	v_mfma_f32_4x4x1_16b_f32 v[36:39], v231, v194, v[36:39]
	v_mfma_f32_4x4x1_16b_f32 v[44:47], v127, v193, v[44:47]
	v_mfma_f32_4x4x1_16b_f32 v[40:43], v232, v194, v[40:43]
	s_waitcnt lgkmcnt(1)
	v_mfma_f32_4x4x1_16b_f32 v[48:51], v128, v193, v[48:51]
	v_mfma_f32_4x4x1_16b_f32 v[44:47], v233, v194, v[44:47]
	v_mfma_f32_4x4x1_16b_f32 v[52:55], v129, v193, v[52:55]
	s_waitcnt lgkmcnt(0)
	v_mfma_f32_4x4x1_16b_f32 v[48:51], v234, v194, v[48:51]
	v_mfma_f32_4x4x1_16b_f32 v[56:59], v130, v193, v[56:59]
	v_mfma_f32_4x4x1_16b_f32 v[52:55], v235, v194, v[52:55]
	v_mfma_f32_4x4x1_16b_f32 v[60:63], v131, v193, v[60:63]
	v_mfma_f32_4x4x1_16b_f32 v[56:59], v236, v194, v[56:59]
	s_nop 0
	v_mfma_f32_4x4x1_16b_f32 v[60:63], v237, v194, v[60:63]
	v_pk_fma_f32 v[158:159], v[136:137], v[0:1], 0 op_sel_hi:[1,1,0]
	v_pk_fma_f32 v[160:161], v[138:139], v[2:3], 0 op_sel_hi:[1,1,0]
	ds_read_b128 v[136:139], v196 offset:15552
	v_pk_fma_f32 v[162:163], v[140:141], v[4:5], 0 op_sel_hi:[1,1,0]
	v_pk_fma_f32 v[164:165], v[142:143], v[6:7], 0 op_sel_hi:[1,1,0]
	ds_read_b128 v[140:143], v196 offset:15568
	v_pk_fma_f32 v[158:159], v[144:145], v[8:9], v[158:159]
	v_pk_fma_f32 v[160:161], v[146:147], v[10:11], v[160:161]
	ds_read_b128 v[144:147], v196 offset:15584
	v_pk_fma_f32 v[162:163], v[148:149], v[12:13], v[162:163]
	v_pk_fma_f32 v[164:165], v[150:151], v[14:15], v[164:165]
	ds_read_b128 v[148:151], v196 offset:15600
	v_pk_fma_f32 v[158:159], v[176:177], v[16:17], v[158:159]
	v_pk_fma_f32 v[160:161], v[178:179], v[18:19], v[160:161]
	v_pk_fma_f32 v[162:163], v[180:181], v[20:21], v[162:163]
	v_pk_fma_f32 v[164:165], v[182:183], v[22:23], v[164:165]
	v_pk_fma_f32 v[158:159], v[184:185], v[24:25], v[158:159]
	v_pk_fma_f32 v[160:161], v[186:187], v[26:27], v[160:161]
	v_pk_fma_f32 v[162:163], v[188:189], v[28:29], v[162:163]
	v_pk_fma_f32 v[164:165], v[190:191], v[30:31], v[164:165]
	v_pk_fma_f32 v[158:159], v[200:201], v[32:33], v[158:159]
	v_pk_fma_f32 v[160:161], v[202:203], v[34:35], v[160:161]
	v_pk_fma_f32 v[162:163], v[204:205], v[36:37], v[162:163]
	v_pk_fma_f32 v[164:165], v[206:207], v[38:39], v[164:165]
	v_pk_fma_f32 v[158:159], v[214:215], v[40:41], v[158:159]
	v_pk_fma_f32 v[160:161], v[216:217], v[42:43], v[160:161]
	v_pk_fma_f32 v[162:163], v[238:239], v[44:45], v[162:163]
	v_pk_fma_f32 v[164:165], v[240:241], v[46:47], v[164:165]
	s_waitcnt lgkmcnt(3)
	v_pk_fma_f32 v[158:159], v[136:137], v[48:49], v[158:159]
	v_pk_fma_f32 v[160:161], v[138:139], v[50:51], v[160:161]
	s_waitcnt lgkmcnt(2)
	v_pk_fma_f32 v[162:163], v[140:141], v[52:53], v[162:163]
	v_pk_fma_f32 v[164:165], v[142:143], v[54:55], v[164:165]
	s_waitcnt lgkmcnt(1)
	v_pk_fma_f32 v[158:159], v[144:145], v[56:57], v[158:159]
	v_pk_fma_f32 v[160:161], v[146:147], v[58:59], v[160:161]
	s_waitcnt lgkmcnt(0)
	v_pk_fma_f32 v[162:163], v[148:149], v[60:61], v[162:163]
	v_pk_fma_f32 v[164:165], v[150:151], v[62:63], v[164:165]
	v_pk_add_f32 v[158:159], v[158:159], v[162:163]
	v_pk_add_f32 v[160:161], v[160:161], v[164:165]
	v_add_f32_e32 v198, v158, v159
	v_add_f32_e32 v192, v160, v161
	v_add_f32_e32 v198, v192, v198
	ds_write_b32 v109, v198 offset:14336
	s_waitcnt lgkmcnt(0)
	s_waitcnt vmcnt(48)
; #define LAS __attribute__((address_space(3)))
; __device__ __forceinline__ unsigned f2bf(float f) { unsigned u = __float_as_uint(f); return (u + 0x7fffu + ((u >> 16) & 1u)) >> 16; }
; __device__ __forceinline__ float frsq(float x) { return __builtin_amdgcn_rsqf(x); }
; #define LDS_WAIT() asm volatile("s_waitcnt lgkmcnt(0)" ::: "memory")
; template <int MODE> __device__ __forceinline__ void rwkv_item(const Params& P, int e, int c, int h, LAS float* slab, int lane) {
;     ...
;         if (MODE == 1) {
;             LDS_WAIT();
; #pragma unroll
;             for (int s = 0; s < SB; ++s) {
;                 const LAS float* st = slab + s * 512;
;                 const float y = st[lane], v = st[320 + lane];
;                 const float mean = wave_sum(y) * (1.f / 64.f), d = y - mean;
;                 const float var = wave_sum(d * d) * (1.f / 64.f);
;                 const float yn = d * frsq(var + 64e-5f) * lnw + lnb;
;                 MIX[(size_t)(tb + s) * D + ch] = (bf16)f2bf((yn + st[384 + lane] * v) * st[448 + lane]);
;             }
;         }
;         LDS_WAIT();
;     }
; template <int MODE> __device__ __forceinline__ void stage_rwkv_scan(const Params& P, int e, LAS unsigned char* lds) {
;     ...
;     for (int it = gw; it < RNCH * 8; it += ngw) rwkv_item<MODE>(P, e, it >> 3, it & 7, slab, lane);
	ds_read_b128 v[192:195], v175
	ds_read_b128 v[196:199], v175 offset:16
	ds_read2st64_b32 v[136:137], v109 offset0:0 offset1:5
	ds_read2st64_b32 v[138:139], v109 offset0:8 offset1:13
	ds_read2st64_b32 v[140:141], v109 offset0:16 offset1:21
	ds_read2st64_b32 v[142:143], v109 offset0:24 offset1:29
	ds_read2st64_b32 v[144:145], v109 offset0:32 offset1:37
	ds_read2st64_b32 v[146:147], v109 offset0:40 offset1:45
	ds_read2st64_b32 v[148:149], v109 offset0:48 offset1:53
	ds_read2st64_b32 v[150:151], v109 offset0:56 offset1:61
	s_waitcnt lgkmcnt(8)
	v_add_f32_e32 v192, v192, v193
	v_add_f32_e32 v194, v194, v195
	v_add_f32_e32 v196, v196, v197
	v_add_f32_e32 v198, v198, v199
	v_add_f32_e32 v192, v192, v194
	v_add_f32_e32 v196, v196, v198
	v_add_f32_e32 v192, v192, v196
	s_nop 1
	v_add_f32_dpp v192, v192, v192 quad_perm:[1,0,3,2] row_mask:0xf bank_mask:0xf bound_ctrl:1
	s_nop 1
	v_add_f32_dpp v192, v192, v192 quad_perm:[2,3,0,1] row_mask:0xf bank_mask:0xf bound_ctrl:1
	s_nop 1
	v_add_f32_dpp v192, v192, v192 row_half_mirror row_mask:0xf bank_mask:0xf bound_ctrl:1
	ds_write_b32 v208, v192
	s_waitcnt lgkmcnt(0)
	ds_read_b128 v[184:187], v209
	ds_read_b128 v[188:191], v209 offset:16
	s_waitcnt lgkmcnt(0)
	v_fmamk_f32 v136, v184, 0xbc800000, v136
	v_mul_f32_e32 v124, v136, v136
	ds_write_b32 v109, v124
	v_fmamk_f32 v138, v185, 0xbc800000, v138
	v_mul_f32_e32 v124, v138, v138
	ds_write_b32 v109, v124 offset:2048
	v_fmamk_f32 v140, v186, 0xbc800000, v140
	v_mul_f32_e32 v124, v140, v140
	ds_write_b32 v109, v124 offset:4096
	v_fmamk_f32 v142, v187, 0xbc800000, v142
	v_mul_f32_e32 v124, v142, v142
	ds_write_b32 v109, v124 offset:6144
	v_fmamk_f32 v144, v188, 0xbc800000, v144
	v_mul_f32_e32 v124, v144, v144
	ds_write_b32 v109, v124 offset:8192
	v_fmamk_f32 v146, v189, 0xbc800000, v146
	v_mul_f32_e32 v124, v146, v146
	ds_write_b32 v109, v124 offset:10240
	v_fmamk_f32 v148, v190, 0xbc800000, v148
	v_mul_f32_e32 v124, v148, v148
	ds_write_b32 v109, v124 offset:12288
	v_fmamk_f32 v150, v191, 0xbc800000, v150
	v_mul_f32_e32 v124, v150, v150
	ds_write_b32 v109, v124 offset:14336
	s_waitcnt lgkmcnt(0)
	ds_read_b128 v[192:195], v175
	ds_read_b128 v[196:199], v175 offset:16
	s_waitcnt lgkmcnt(0)
	v_add_f32_e32 v192, v192, v193
	v_add_f32_e32 v194, v194, v195
	v_add_f32_e32 v196, v196, v197
	v_add_f32_e32 v198, v198, v199
	v_add_f32_e32 v192, v192, v194
	v_add_f32_e32 v196, v196, v198
	v_add_f32_e32 v192, v192, v196
	s_nop 1
	v_add_f32_dpp v192, v192, v192 quad_perm:[1,0,3,2] row_mask:0xf bank_mask:0xf bound_ctrl:1
	s_nop 1
	v_add_f32_dpp v192, v192, v192 quad_perm:[2,3,0,1] row_mask:0xf bank_mask:0xf bound_ctrl:1
	s_nop 1
	v_add_f32_dpp v192, v192, v192 row_half_mirror row_mask:0xf bank_mask:0xf bound_ctrl:1
	ds_write_b32 v208, v192
	s_waitcnt lgkmcnt(0)
	ds_read_b128 v[184:187], v209
	ds_read_b128 v[188:191], v209 offset:16
	ds_read2st64_b32 v[128:129], v109 offset0:6 offset1:7
	ds_read2st64_b32 v[130:131], v109 offset0:14 offset1:15
	ds_read2st64_b32 v[132:133], v109 offset0:22 offset1:23
	ds_read2st64_b32 v[134:135], v109 offset0:30 offset1:31
	ds_read2st64_b32 v[192:193], v109 offset0:38 offset1:39
	ds_read2st64_b32 v[194:195], v109 offset0:46 offset1:47
	ds_read2st64_b32 v[196:197], v109 offset0:54 offset1:55
	ds_read2st64_b32 v[198:199], v109 offset0:62 offset1:63
	s_waitcnt lgkmcnt(7)
	v_fmamk_f32 v124, v184, 0x3c800000, v221
	v_rsq_f32_e32 v124, v124
	v_add_u32_e32 v127, 0x0, v113
	v_mul_f32_e32 v136, v136, v124
	v_fma_f32 v136, v120, v136, v121
	v_fmac_f32_e32 v136, v137, v128
	v_mul_f32_e32 v136, v129, v136
	v_bfe_u32 v125, v136, 16, 1
	v_add3_u32 v126, v136, v125, s33
	global_store_short_d16_hi v127, v126, s[70:71]
	s_waitcnt lgkmcnt(6)
	v_fmamk_f32 v124, v185, 0x3c800000, v221
	v_rsq_f32_e32 v124, v124
	v_add_u32_e32 v127, 0x800, v113
	v_mul_f32_e32 v138, v138, v124
	v_fma_f32 v138, v120, v138, v121
	v_fmac_f32_e32 v138, v139, v130
	v_mul_f32_e32 v138, v131, v138
	v_bfe_u32 v125, v138, 16, 1
	v_add3_u32 v126, v138, v125, s33
	global_store_short_d16_hi v127, v126, s[70:71]
	s_waitcnt lgkmcnt(5)
	v_fmamk_f32 v124, v186, 0x3c800000, v221
	v_rsq_f32_e32 v124, v124
	v_add_u32_e32 v127, 0x1000, v113
	v_mul_f32_e32 v140, v140, v124
	v_fma_f32 v140, v120, v140, v121
	v_fmac_f32_e32 v140, v141, v132
	v_mul_f32_e32 v140, v133, v140
	v_bfe_u32 v125, v140, 16, 1
	v_add3_u32 v126, v140, v125, s33
	global_store_short_d16_hi v127, v126, s[70:71]
	s_waitcnt lgkmcnt(4)
	v_fmamk_f32 v124, v187, 0x3c800000, v221
	v_rsq_f32_e32 v124, v124
	v_add_u32_e32 v127, 0x1800, v113
	v_mul_f32_e32 v142, v142, v124
	v_fma_f32 v142, v120, v142, v121
	v_fmac_f32_e32 v142, v143, v134
	v_mul_f32_e32 v142, v135, v142
	v_bfe_u32 v125, v142, 16, 1
	v_add3_u32 v126, v142, v125, s33
	global_store_short_d16_hi v127, v126, s[70:71]
	s_waitcnt lgkmcnt(3)
	v_fmamk_f32 v124, v188, 0x3c800000, v221
	v_rsq_f32_e32 v124, v124
	v_add_u32_e32 v127, 0x2000, v113
	v_mul_f32_e32 v144, v144, v124
	v_fma_f32 v144, v120, v144, v121
	v_fmac_f32_e32 v144, v145, v192
	v_mul_f32_e32 v144, v193, v144
	v_bfe_u32 v125, v144, 16, 1
	v_add3_u32 v126, v144, v125, s33
	global_store_short_d16_hi v127, v126, s[70:71]
	s_waitcnt lgkmcnt(2)
	v_fmamk_f32 v124, v189, 0x3c800000, v221
	v_rsq_f32_e32 v124, v124
	v_add_u32_e32 v127, 0x2800, v113
	v_mul_f32_e32 v146, v146, v124
	v_fma_f32 v146, v120, v146, v121
	v_fmac_f32_e32 v146, v147, v194
	v_mul_f32_e32 v146, v195, v146
	v_bfe_u32 v125, v146, 16, 1
	v_add3_u32 v126, v146, v125, s33
	global_store_short_d16_hi v127, v126, s[70:71]
	s_waitcnt lgkmcnt(1)
	v_fmamk_f32 v124, v190, 0x3c800000, v221
	v_rsq_f32_e32 v124, v124
	v_add_u32_e32 v127, 0x3000, v113
	v_mul_f32_e32 v148, v148, v124
	v_fma_f32 v148, v120, v148, v121
	v_fmac_f32_e32 v148, v149, v196
	v_mul_f32_e32 v148, v197, v148
	v_bfe_u32 v125, v148, 16, 1
	v_add3_u32 v126, v148, v125, s33
	global_store_short_d16_hi v127, v126, s[70:71]
	s_waitcnt lgkmcnt(0)
	v_fmamk_f32 v124, v191, 0x3c800000, v221
	v_rsq_f32_e32 v124, v124
	v_add_u32_e32 v127, 0x3800, v113
	v_mul_f32_e32 v150, v150, v124
	v_fma_f32 v150, v120, v150, v121
	v_fmac_f32_e32 v150, v151, v198
	v_mul_f32_e32 v150, v199, v150
	v_bfe_u32 v125, v150, 16, 1
	v_add3_u32 v126, v150, v125, s33
	global_store_short_d16_hi v127, v126, s[70:71]
	v_add_u32_e32 v113, 0x4000, v113
	s_add_i32 s1, s1, 1
	s_cmp_eq_u32 s1, 8
	s_cbranch_scc0 .Lm1_sub
	s_add_i32 s2, s2, s58
	s_cmpk_gt_i32 s2, 0x7ff
	s_cbranch_scc0 .LBB0_205
	s_load_dwordx2 s[72:73], s[30:31], 0x118
	v_readlane_b32 s12, v253, 17
	v_readlane_b32 s13, v253, 18
	v_readlane_b32 s67, v255, 14
	v_readlane_b32 s71, v255, 15
	v_readlane_b32 s51, v255, 16
